# diff+GQA attention loops hand-written: -m folded into MFMA C-init (diff), no per-tile max tree (tile-sum overflow check, exact path on trigger), in-place exp/cvt; GEMM EPI_M k-loop DMA issue staggered
# speedup vs baseline: 1.0455x; 1.0187x over previous
; __global__ void __launch_bounds__(NTHR) mega(Params p, int ph0, int ph1) {
;   __shared__ __attribute__((aligned(16))) char lds[LDS_BYTES];
;   unsigned* bar = (unsigned*)(p.ws + OFF_BAR);
;   if (ph0 == 0 && blockIdx.x == 0 && threadIdx.x < 9)
;     __hip_atomic_store((unsigned*)(p.ws + OFF_BAR + 256 * threadIdx.x), 0u, __ATOMIC_RELAXED, __HIP_MEMORY_SCOPE_AGENT);
;   if (ph0 == 0 && blockIdx.x == 0 && threadIdx.x >= 64 && threadIdx.x < 128) ((unsigned*)(p.ws + OFF_ZERO))[threadIdx.x - 64] = 0u;
;   unsigned nbar = 0;
;   for (int ph = ph0; ph < ph1; ++ph) {
;     if (ph > ph0) {
;       if (ph == ph0 + 1) cg::this_grid().sync();
;       else { ++nbar; grid_barrier(bar, nbar * gridDim.x); }
;     }
;     const u16* H = (const u16*)(p.ws + OFF_H);
;     u16* Hm = (u16*)(p.ws + OFF_H);
;     const u16* Abuf = (const u16*)(p.ws + OFF_BIG);
;     u16* Bm = (u16*)(p.ws + OFF_BIG);
;     switch (ph) {
.LBB0_7:
	s_add_i32 s3, s14, 1
	s_add_u32 s74, s0, 0xb8
	s_addc_u32 s75, s1, 0
	v_and_b32_e32 v204, 0x3ff, v0
	s_load_dwordx8 s[4:11], s[0:1], 0x80
	s_load_dwordx16 s[16:31], s[0:1], 0x0
	s_load_dwordx16 s[36:51], s[0:1], 0x40
	v_writelane_b32 v253, s3, 0
	v_cmp_eq_u32_e64 s[0:1], 0, v204
	s_add_u32 s90, s70, 0x37f8000
	v_and_b32_e32 v0, 0x3fffffff, v0
	v_writelane_b32 v253, s0, 1
	s_addc_u32 s91, s71, 0
	s_add_u32 s2, s70, 0x97f8000
	v_writelane_b32 v253, s1, 2
	v_cmp_eq_u32_e64 s[0:1], 0, v0
	s_addc_u32 s3, s71, 0
	s_mov_b32 s99, 0
	v_writelane_b32 v253, s0, 3
	s_mov_b32 s35, s99
	v_mbcnt_lo_u32_b32 v0, -1, 0
	v_writelane_b32 v253, s1, 4
	s_add_u32 s0, s70, 0x2200000
	s_addc_u32 s1, s71, 0
	v_writelane_b32 v253, s0, 5
	v_mbcnt_hi_u32_b32 v207, -1, v0
	v_and_b32_e32 v0, 64, v207
	v_writelane_b32 v253, s1, 6
	s_add_u32 s0, s70, 0x2d80000
	s_addc_u32 s1, s71, 0
	v_writelane_b32 v253, s0, 7
	s_mov_b32 s84, s14
	s_mov_b64 s[86:87], 0x5800
	v_writelane_b32 v253, s1, 8
	s_add_u32 s0, s70, 0x1c80000
	s_addc_u32 s1, s71, 0
	v_writelane_b32 v253, s0, 9
	v_mov_b32_e32 v1, 0
	s_mov_b32 s33, 0xc000
	v_writelane_b32 v253, s1, 10
	s_add_u32 s0, s70, 0x480000
	s_addc_u32 s1, s71, 0
	v_writelane_b32 v253, s0, 11
	s_and_b32 s67, s34, 7
	v_mov_b32_e32 v205, 0x358637bd
	v_writelane_b32 v253, s1, 12
	s_ashr_i32 s0, s34, 3
	s_add_u32 s80, s70, 0x1d7f9000
	v_writelane_b32 v253, s0, 13
	s_addc_u32 s81, s71, 0
	s_lshl_b32 s0, s34, 3
	v_writelane_b32 v253, s0, 14
	s_add_u32 s0, s70, 0x2f85000
	s_addc_u32 s1, s71, 0
	v_writelane_b32 v253, s0, 15
	s_movk_i32 s66, 0x70
	s_mov_b64 s[56:57], 0x37f8080
	v_writelane_b32 v253, s1, 16
	s_add_u32 s0, s70, 0x1180000
	s_addc_u32 s1, s71, 0
	v_writelane_b32 v253, s0, 17
	s_mov_b64 s[60:61], 0x3818080
	s_mov_b64 s[54:55], 0x27a0080
	v_writelane_b32 v253, s1, 18
	s_waitcnt lgkmcnt(0)
; __global__ void __launch_bounds__(NTHR) mega(Params p, int ph0, int ph1) {
;   __shared__ __attribute__((aligned(16))) char lds[LDS_BYTES];
;   unsigned* bar = (unsigned*)(p.ws + OFF_BAR);
;   if (ph0 == 0 && blockIdx.x == 0 && threadIdx.x < 9)
;     __hip_atomic_store((unsigned*)(p.ws + OFF_BAR + 256 * threadIdx.x), 0u, __ATOMIC_RELAXED, __HIP_MEMORY_SCOPE_AGENT);
;   if (ph0 == 0 && blockIdx.x == 0 && threadIdx.x >= 64 && threadIdx.x < 128) ((unsigned*)(p.ws + OFF_ZERO))[threadIdx.x - 64] = 0u;
;   unsigned nbar = 0;
;   for (int ph = ph0; ph < ph1; ++ph) {
;     if (ph > ph0) {
;       if (ph == ph0 + 1) cg::this_grid().sync();
;       else { ++nbar; grid_barrier(bar, nbar * gridDim.x); }
;     }
;     const u16* H = (const u16*)(p.ws + OFF_H);
;     u16* Hm = (u16*)(p.ws + OFF_H);
;     const u16* Abuf = (const u16*)(p.ws + OFF_BIG);
;     u16* Bm = (u16*)(p.ws + OFF_BIG);
;     switch (ph) {
	s_add_u32 s0, s4, 0x10800
	s_addc_u32 s1, s5, 0
	v_writelane_b32 v253, s0, 19
	s_mov_b64 s[52:53], 0x3838080
	s_mov_b64 s[76:77], 0x37f8100
	v_writelane_b32 v253, s1, 20
	s_add_u32 s0, s4, 0x13400
	s_addc_u32 s1, s5, 0
	v_writelane_b32 v253, s0, 21
	s_mov_b64 s[92:93], 0x3818100
	s_mov_b64 s[94:95], 0x3838100
	v_writelane_b32 v253, s1, 22
	s_add_u32 s0, s4, 0x16000
	s_addc_u32 s1, s5, 0
	v_writelane_b32 v253, s0, 23
	s_mov_b64 s[96:97], 0x3858100
	s_mov_b32 s85, 0x20000
	v_writelane_b32 v253, s1, 24
	s_add_u32 s0, s4, 0x18c00
	s_addc_u32 s1, s5, 0
	v_writelane_b32 v253, s0, 25
	s_mov_b64 s[82:83], 0x34000
	v_mov_b32_e32 v206, 0x3727c5ac
	v_writelane_b32 v253, s1, 26
	s_add_u32 s0, s4, 0x1b800
	s_addc_u32 s1, s5, 0
	v_writelane_b32 v253, s0, 27
	s_mov_b64 s[78:79], 0x20080
	s_mov_b64 s[58:59], 0x40080
	v_writelane_b32 v253, s1, 28
	s_add_u32 s0, s4, 0x1e400
	s_addc_u32 s1, s5, 0
	v_writelane_b32 v253, s0, 29
	s_mov_b64 s[62:63], 0x60080
	v_add_u32_e32 v208, 64, v0
	v_writelane_b32 v253, s1, 30
	s_add_u32 s0, s6, 0x5800
	s_addc_u32 s1, s7, 0
	v_writelane_b32 v253, s0, 31
	v_xor_b32_e32 v209, 1, v207
	v_xor_b32_e32 v250, 2, v207
	v_writelane_b32 v253, s1, 32
	s_add_u32 s0, s6, 0x8400
	s_addc_u32 s1, s7, 0
	v_writelane_b32 v253, s0, 33
	v_xor_b32_e32 v251, 4, v207
	v_xor_b32_e32 v252, 8, v207
	v_writelane_b32 v253, s1, 34
	s_add_u32 s0, s28, 0x3000
	s_addc_u32 s1, s29, 0
	v_writelane_b32 v253, s0, 35
	v_xor_b32_e32 v225, 16, v207
	v_xor_b32_e32 v214, 32, v207
	v_writelane_b32 v253, s1, 36
	s_add_u32 s0, s70, 0x2f83000
	s_addc_u32 s1, s71, 0
	v_writelane_b32 v253, s0, 37
	v_mov_b32_e32 v215, 0xf000
	v_mov_b32_e32 v216, 0x1600
	v_writelane_b32 v253, s1, 38
	s_add_u32 s0, s70, 0x2f82000
	s_addc_u32 s1, s71, 0
	v_writelane_b32 v253, s0, 39
	v_mov_b32_e32 v217, 0x7ff
	v_mov_b32_e32 v218, 0x3fff
	v_writelane_b32 v253, s1, 40
	s_add_u32 s0, s70, 0x157f8000
	v_writelane_b32 v253, s0, 41
	s_addc_u32 s0, s71, 0
	s_add_u32 s12, s70, 0x2780000
	v_writelane_b32 v253, s0, 42
	s_addc_u32 s13, s71, 0
	v_writelane_b32 v253, s12, 43
	v_mov_b32_e32 v219, 0x3e38aa3b
	v_mov_b32_e32 v184, 0xd000
	v_writelane_b32 v253, s13, 44
	s_add_u32 s12, s28, 0x2000
	s_addc_u32 s13, s29, 0
	s_add_u32 s88, s70, 0x2f80000
	v_writelane_b32 v253, s12, 45
	s_addc_u32 s89, s71, 0
	v_mov_b32_e32 v220, 0x7000
	v_writelane_b32 v253, s13, 46
	s_add_u32 s12, s70, 0x680000
	s_addc_u32 s13, s71, 0
	v_writelane_b32 v253, s12, 47
	v_mov_b32_e32 v221, 0x800
	v_mov_b32_e32 v222, 0x4000
	v_writelane_b32 v253, s13, 48
	s_add_u32 s12, s4, 0x2c00
	s_addc_u32 s13, s5, 0
	v_writelane_b32 v253, s12, 49
	v_mov_b32_e32 v223, 0x2ff8000
	v_mov_b32_e32 v224, 0x33f8000
	v_writelane_b32 v253, s13, 50
	s_add_u32 s12, s4, 0x5800
	s_addc_u32 s13, s5, 0
	v_writelane_b32 v253, s12, 51
	s_nop 1
	v_writelane_b32 v253, s13, 52
	s_add_u32 s12, s4, 0x8400
	s_addc_u32 s13, s5, 0
	v_writelane_b32 v253, s12, 53
	s_nop 1
	v_writelane_b32 v253, s13, 54
	s_add_u32 s12, s4, 0xb000
	s_addc_u32 s13, s5, 0
	v_writelane_b32 v253, s12, 55
	s_nop 1
	v_writelane_b32 v253, s13, 56
	s_add_u32 s12, s4, 0xdc00
	s_addc_u32 s13, s5, 0
	v_writelane_b32 v253, s12, 57
	s_nop 1
	v_writelane_b32 v253, s13, 58
	s_add_u32 s12, s6, 0x2c00
	s_addc_u32 s13, s7, 0
	v_writelane_b32 v253, s12, 59
	s_nop 1
	v_writelane_b32 v253, s13, 60
	s_add_u32 s12, s28, 0x1000
	s_addc_u32 s13, s29, 0
	v_writelane_b32 v253, s12, 61
	s_nop 1
	v_writelane_b32 v253, s13, 62
	s_lshl_b64 s[12:13], s[34:35], 9
	s_add_u32 s0, s70, 0x133f8000
	v_writelane_b32 v253, s12, 63
	s_addc_u32 s1, s71, 0
	s_nop 0
	v_writelane_b32 v254, s13, 0
	v_writelane_b32 v254, s0, 1
	s_nop 1
	v_writelane_b32 v254, s1, 2
	s_add_u32 s0, s70, 0x1b7f8000
	s_addc_u32 s1, s71, 0
	v_writelane_b32 v254, s0, 3
	s_nop 1
	v_writelane_b32 v254, s1, 4
	s_lshl_b32 s0, s34, 8
	s_and_b32 s0, s0, 0x700
	s_add_u32 s0, s70, s0
	s_addc_u32 s1, s71, 0
	s_add_u32 s0, s0, 0x1d7f8100
	s_addc_u32 s1, s1, 0
	v_writelane_b32 v254, s0, 5
	s_cmpk_lt_i32 s34, 0x1980
	s_nop 0
	v_writelane_b32 v254, s1, 6
	s_mov_b32 s0, s34
	v_writelane_b32 v254, s0, 7
	s_nop 1
	v_writelane_b32 v254, s1, 8
	s_cselect_b64 s[0:1], -1, 0
	v_writelane_b32 v254, s0, 9
	s_nop 1
	v_writelane_b32 v254, s1, 10
	s_add_u32 s0, s8, 0xb00000
	v_writelane_b32 v254, s4, 11
	s_addc_u32 s1, s9, 0
	s_nop 0
	v_writelane_b32 v254, s5, 12
	v_writelane_b32 v254, s6, 13
	v_writelane_b32 v254, s7, 14
	v_writelane_b32 v254, s8, 15
	v_writelane_b32 v254, s9, 16
	v_writelane_b32 v254, s10, 17
	v_writelane_b32 v254, s11, 18
	v_writelane_b32 v254, s0, 19
	s_mov_b32 s6, 0
	s_mov_b64 s[4:5], 0x80
	v_writelane_b32 v254, s1, 20
	s_add_u32 s0, s50, 0x1600000
	v_writelane_b32 v254, s36, 21
	s_addc_u32 s1, s51, 0
	s_nop 0
	v_writelane_b32 v254, s37, 22
	v_writelane_b32 v254, s38, 23
	v_writelane_b32 v254, s39, 24
	v_writelane_b32 v254, s40, 25
	v_writelane_b32 v254, s41, 26
	v_writelane_b32 v254, s42, 27
	v_writelane_b32 v254, s43, 28
	v_writelane_b32 v254, s44, 29
	v_writelane_b32 v254, s45, 30
	v_writelane_b32 v254, s46, 31
	v_writelane_b32 v254, s47, 32
	v_writelane_b32 v254, s48, 33
	v_writelane_b32 v254, s49, 34
	v_writelane_b32 v254, s50, 35
	v_writelane_b32 v254, s51, 36
	v_writelane_b32 v254, s0, 37
	s_mov_b64 s[44:45], 0x1000
	s_mov_b32 s48, 0x8000
	v_writelane_b32 v254, s1, 38
	s_add_u32 s0, s68, 0xc00
	s_addc_u32 s1, s69, 0
	v_writelane_b32 v254, s0, 39
	s_mov_b32 s49, 0x800000
	s_movk_i32 s50, 0x100
	v_writelane_b32 v254, s1, 40
	s_add_u32 s0, s70, 0x97fac00
	s_addc_u32 s1, s71, 0
	v_writelane_b32 v254, s0, 41
	s_mov_b32 s51, 0x1ffff80
	s_mov_b64 s[42:43], 0x3818900
	v_writelane_b32 v254, s1, 42
	s_add_u32 s0, s70, 0x97f9600
	s_addc_u32 s1, s71, 0
	v_writelane_b32 v254, s0, 43
	s_mov_b64 s[40:41], 0x3838900
	s_mov_b64 s[38:39], 0x3858900
	v_writelane_b32 v254, s1, 44
	s_add_u32 s0, s70, 0x133f8100
	s_addc_u32 s1, s71, 0
	v_writelane_b32 v254, s0, 45
	s_mov_b64 s[46:47], 0x2780080
	s_mov_b64 s[36:37], 0x27c0080
	v_writelane_b32 v254, s1, 46
	s_add_u32 s0, s70, 0x9860c00
	s_addc_u32 s1, s71, 0
	v_writelane_b32 v254, s0, 47
	s_nop 1
	v_writelane_b32 v254, s1, 48
	s_add_u32 s0, s70, 0x9860400
	s_addc_u32 s1, s71, 0
	v_writelane_b32 v254, s0, 49
	s_nop 1
	v_writelane_b32 v254, s1, 50
	v_writelane_b32 v254, s6, 51
	v_writelane_b32 v254, s16, 52
	s_mov_b64 s[0:1], 0x3858080
	s_nop 0
	v_writelane_b32 v254, s17, 53
	v_writelane_b32 v254, s18, 54
	v_writelane_b32 v254, s19, 55
	v_writelane_b32 v254, s20, 56
	v_writelane_b32 v254, s21, 57
	v_writelane_b32 v254, s22, 58
	v_writelane_b32 v255, s28, 0
	v_writelane_b32 v254, s23, 59
	v_writelane_b32 v255, s29, 1
	v_writelane_b32 v254, s24, 60
	v_writelane_b32 v255, s30, 2
	v_writelane_b32 v254, s25, 61
	v_writelane_b32 v255, s31, 3
	v_writelane_b32 v254, s26, 62
	v_writelane_b32 v255, s14, 4
	v_writelane_b32 v254, s27, 63
	s_nop 0
	v_writelane_b32 v255, s15, 5
	v_readfirstlane_b32 s101, v204
	s_nop 0
	s_lshr_b32 s101, s101, 8
	s_branch .LBB0_10

; template <bool SWAP>
; DI void gemm_mainloop(f32x16 (&acc)[4][2], const u16* __restrict__ A, int lda, int rlo, int rhi,
;                       const u16* __restrict__ B, int ldb, int K, char* lds, const u16* zero_line) {
;     ...
;   auto glds = [&](int kt, int st) {
;     char* as_ = lds + st * 65536 + tid * 16;
; #pragma unroll
;     for (int i = 0; i < 4; ++i) {
;       const int rr = lr + 64 * i;
;       const u16* srca = (rr >= rlo && rr < rhi) ? (ap + (ptrdiff_t)(64 * i) * lda + kt * 64) : (zero_line + lc * 8);
;       __builtin_amdgcn_global_load_lds((const unsigned*)srca, (lds_u32*)(as_ + i * 8192), 16, 0, 0);
;       __builtin_amdgcn_global_load_lds((const unsigned*)(bp + (ptrdiff_t)(64 * i) * ldb + kt * 64), (lds_u32*)(as_ + 32768 + i * 8192), 16, 0, 0);
;     }
;   };
;     ...
;   auto pat_rd = [&]() {
; #pragma unroll
;     for (int g = 0; g < 6; ++g) {
;       __builtin_amdgcn_sched_group_barrier(0x100, 1, 0);
;       __builtin_amdgcn_sched_group_barrier(0x008, 1, 0);
;     }
;     __builtin_amdgcn_sched_group_barrier(0x008, 2, 0);
;   };
; #pragma unroll 2
;   for (int kt = 0; kt < nk; ++kt) {
;     const char* st = lds + (kt & 1) * 65536;
;     ldfrag(st, 0, 0);
;     mma(1);
;     pat_rd();
;     if (kt + 1 < nk) glds(kt + 1, (kt + 1) & 1);
;     ldfrag(st, 1, 1);
;     mma(0);
;     pat_rd();
;     ldfrag(st, 2, 0);
;     mma(1);
;     pat_rd();
;     ldfrag(st, 3, 1);
;     mma(0);
;     pat_rd();
;     asm volatile("s_waitcnt vmcnt(0)" ::: "memory");
;     __syncthreads();
.LBB0_246:
	s_add_i32 s35, s25, 0xffff0000
	s_and_b32 s35, s35, 0x10000
	v_add_u32_e32 v229, s35, v203
	v_or_b32_e32 v230, s35, v202
	v_add_u32_e32 v154, v229, v228
	v_add_u32_e32 v162, v230, v228
	s_and_b32 s35, s25, 0x10000
	ds_read_b128 v[174:177], v154
	v_mfma_f32_32x32x16_bf16 v[114:129], v[146:149], v[150:153], v[114:129]
	ds_read_b128 v[170:173], v154 offset:4096
	s_cmp_eq_u32 s101, 1
	s_cbranch_scc1 .Lg246_skipA
	v_add_u32_e32 v234, s35, v226
	v_add_u32_e32 v235, 0x8000, v234
	v_lshl_add_u64 v[232:233], v[182:183], 0, v[0:1]
	v_readfirstlane_b32 s36, v234
	v_cndmask_b32_e32 v233, v181, v233, vcc
	v_cndmask_b32_e32 v232, v180, v232, vcc
	s_mov_b32 m0, s36
	v_readfirstlane_b32 s36, v235
	global_load_lds_dwordx4 v[232:233], off
	v_lshl_add_u64 v[232:233], v[186:187], 0, v[0:1]
	s_mov_b32 m0, s36
	v_add_u32_e32 v235, 0x2000, v234
	global_load_lds_dwordx4 v[232:233], off
	v_lshl_add_u64 v[232:233], v[188:189], 0, v[0:1]
	v_readfirstlane_b32 s36, v235
	v_add_u32_e32 v235, 0xa000, v234
	v_cndmask_b32_e64 v233, v181, v233, s[6:7]
	v_cndmask_b32_e64 v232, v180, v232, s[6:7]
	s_mov_b32 m0, s36
	v_readfirstlane_b32 s36, v235
	global_load_lds_dwordx4 v[232:233], off
	v_lshl_add_u64 v[232:233], v[190:191], 0, v[0:1]
	s_mov_b32 m0, s36
	v_add_u32_e32 v235, 0x4000, v234
	global_load_lds_dwordx4 v[232:233], off
	v_lshl_add_u64 v[232:233], v[192:193], 0, v[0:1]
	v_readfirstlane_b32 s36, v235
	v_add_u32_e32 v235, 0xc000, v234
	v_cndmask_b32_e64 v233, v181, v233, s[8:9]
	v_cndmask_b32_e64 v232, v180, v232, s[8:9]
	s_mov_b32 m0, s36
	v_readfirstlane_b32 s36, v235
	global_load_lds_dwordx4 v[232:233], off
	v_lshl_add_u64 v[232:233], v[194:195], 0, v[0:1]
	s_mov_b32 m0, s36
	v_add_u32_e32 v235, 0x6000, v234
	global_load_lds_dwordx4 v[232:233], off
	v_lshl_add_u64 v[232:233], v[196:197], 0, v[0:1]
	v_readfirstlane_b32 s36, v235
	v_add_u32_e32 v234, 0xe000, v234
	v_cndmask_b32_e64 v233, v181, v233, s[10:11]
	v_cndmask_b32_e64 v232, v180, v232, s[10:11]
	s_mov_b32 m0, s36
	v_readfirstlane_b32 s36, v234
	global_load_lds_dwordx4 v[232:233], off
	v_lshl_add_u64 v[232:233], v[198:199], 0, v[0:1]
	s_mov_b32 m0, s36
	v_lshl_add_u64 v[182:183], v[182:183], 0, s[4:5]
	global_load_lds_dwordx4 v[232:233], off
.Lg246_skipA:
	s_add_i32 s25, s25, 0x10000
	v_mfma_f32_32x32x16_bf16 v[98:113], v[138:141], v[150:153], v[98:113]
	ds_read_b128 v[158:161], v154 offset:8192
	v_add_u32_e32 v150, v230, v227
	v_mfma_f32_32x32x16_bf16 v[82:97], v[146:149], v[142:145], v[82:97]
	ds_read_b128 v[154:157], v154 offset:12288
	v_mfma_f32_32x32x16_bf16 v[66:81], v[138:141], v[142:145], v[66:81]
	ds_read_b128 v[166:169], v162 offset:32768
	v_add_u32_e32 v142, v229, v227
	v_mfma_f32_32x32x16_bf16 v[50:65], v[146:149], v[134:137], v[50:65]
	ds_read_b128 v[162:165], v162 offset:36864
	v_mfma_f32_32x32x16_bf16 v[34:49], v[138:141], v[134:137], v[34:49]
	v_mfma_f32_32x32x16_bf16 v[18:33], v[146:149], v[130:133], v[18:33]
	v_mfma_f32_32x32x16_bf16 v[2:17], v[138:141], v[130:133], v[2:17]
	ds_read_b128 v[130:133], v142
	s_waitcnt lgkmcnt(0)
	v_mfma_f32_32x32x16_bf16 v[114:129], v[166:169], v[174:177], v[114:129]
	ds_read_b128 v[134:137], v142 offset:4096
	v_mfma_f32_32x32x16_bf16 v[98:113], v[162:165], v[174:177], v[98:113]
	ds_read_b128 v[138:141], v142 offset:8192
	v_add_u32_e32 v174, v230, v201
	v_mfma_f32_32x32x16_bf16 v[82:97], v[166:169], v[170:173], v[82:97]
	ds_read_b128 v[142:145], v142 offset:12288
	v_mfma_f32_32x32x16_bf16 v[66:81], v[162:165], v[170:173], v[66:81]
	ds_read_b128 v[146:149], v150 offset:32768
	v_mfma_f32_32x32x16_bf16 v[50:65], v[166:169], v[158:161], v[50:65]
	ds_read_b128 v[150:153], v150 offset:36864
	v_mfma_f32_32x32x16_bf16 v[34:49], v[162:165], v[158:161], v[34:49]
	v_mfma_f32_32x32x16_bf16 v[18:33], v[166:169], v[154:157], v[18:33]
	v_add_u32_e32 v166, v229, v201
	v_mfma_f32_32x32x16_bf16 v[2:17], v[162:165], v[154:157], v[2:17]
	ds_read_b128 v[154:157], v166
	s_cmp_eq_u32 s101, 0
	s_cbranch_scc1 .Lg246_skipB
	v_add_u32_e32 v234, s35, v226
	v_add_u32_e32 v235, 0x8000, v234
	v_lshl_add_u64 v[232:233], v[182:183], 0, v[0:1]
	v_readfirstlane_b32 s36, v234
	v_cndmask_b32_e32 v233, v181, v233, vcc
	v_cndmask_b32_e32 v232, v180, v232, vcc
	s_mov_b32 m0, s36
	v_readfirstlane_b32 s36, v235
	global_load_lds_dwordx4 v[232:233], off
	v_lshl_add_u64 v[232:233], v[186:187], 0, v[0:1]
	s_mov_b32 m0, s36
	v_add_u32_e32 v235, 0x2000, v234
	global_load_lds_dwordx4 v[232:233], off
	v_lshl_add_u64 v[232:233], v[188:189], 0, v[0:1]
	v_readfirstlane_b32 s36, v235
	v_add_u32_e32 v235, 0xa000, v234
	v_cndmask_b32_e64 v233, v181, v233, s[6:7]
	v_cndmask_b32_e64 v232, v180, v232, s[6:7]
	s_mov_b32 m0, s36
	v_readfirstlane_b32 s36, v235
	global_load_lds_dwordx4 v[232:233], off
	v_lshl_add_u64 v[232:233], v[190:191], 0, v[0:1]
	s_mov_b32 m0, s36
	v_add_u32_e32 v235, 0x4000, v234
	global_load_lds_dwordx4 v[232:233], off
	v_lshl_add_u64 v[232:233], v[192:193], 0, v[0:1]
	v_readfirstlane_b32 s36, v235
	v_add_u32_e32 v235, 0xc000, v234
	v_cndmask_b32_e64 v233, v181, v233, s[8:9]
	v_cndmask_b32_e64 v232, v180, v232, s[8:9]
	s_mov_b32 m0, s36
	v_readfirstlane_b32 s36, v235
	global_load_lds_dwordx4 v[232:233], off
	v_lshl_add_u64 v[232:233], v[194:195], 0, v[0:1]
	s_mov_b32 m0, s36
	v_add_u32_e32 v235, 0x6000, v234
	global_load_lds_dwordx4 v[232:233], off
	v_lshl_add_u64 v[232:233], v[196:197], 0, v[0:1]
	v_readfirstlane_b32 s36, v235
	v_add_u32_e32 v234, 0xe000, v234
	v_cndmask_b32_e64 v233, v181, v233, s[10:11]
	v_cndmask_b32_e64 v232, v180, v232, s[10:11]
	s_mov_b32 m0, s36
	v_readfirstlane_b32 s36, v234
	global_load_lds_dwordx4 v[232:233], off
	v_lshl_add_u64 v[232:233], v[198:199], 0, v[0:1]
	s_mov_b32 m0, s36
	v_lshl_add_u64 v[182:183], v[182:183], 0, s[4:5]
	global_load_lds_dwordx4 v[232:233], off
; template <bool SWAP>
; DI void gemm_mainloop(f32x16 (&acc)[4][2], const u16* __restrict__ A, int lda, int rlo, int rhi,
;                       const u16* __restrict__ B, int ldb, int K, char* lds, const u16* zero_line) {
;     ...
; #pragma unroll 2
;   for (int kt = 0; kt < nk; ++kt) {
;     const char* st = lds + (kt & 1) * 65536;
;     ldfrag(st, 0, 0);
;     mma(1);
;     pat_rd();
;     if (kt + 1 < nk) glds(kt + 1, (kt + 1) & 1);
;     ldfrag(st, 1, 1);
;     mma(0);
;     pat_rd();
;     ldfrag(st, 2, 0);
;     mma(1);
;     pat_rd();
;     ldfrag(st, 3, 1);
;     mma(0);
;     pat_rd();
;     asm volatile("s_waitcnt vmcnt(0)" ::: "memory");
;     __syncthreads();
;   }
;   mma(1);
; template <int EPI>
; DI void phase_gemm(const Params& p, const GemmArgs& ga, char* lds) {
;     ...
;     if (EPI == EPI_M) {
;       u16* mo = ga.Mout + (size_t)(tokbase + pos0 + wm * 128 + r) * DM + n0w + 8 * h;
.Lg246_skipB:
	v_lshl_add_u64 v[186:187], v[186:187], 0, s[4:5]
	v_lshl_add_u64 v[188:189], v[188:189], 0, s[4:5]
	v_lshl_add_u64 v[190:191], v[190:191], 0, s[4:5]
	v_lshl_add_u64 v[192:193], v[192:193], 0, s[4:5]
	v_lshl_add_u64 v[194:195], v[194:195], 0, s[4:5]
	v_lshl_add_u64 v[196:197], v[196:197], 0, s[4:5]
	v_lshl_add_u64 v[198:199], v[198:199], 0, s[4:5]
	s_waitcnt lgkmcnt(0)
	v_mfma_f32_32x32x16_bf16 v[114:129], v[146:149], v[130:133], v[114:129]
	ds_read_b128 v[158:161], v166 offset:4096
	v_mfma_f32_32x32x16_bf16 v[98:113], v[150:153], v[130:133], v[98:113]
	ds_read_b128 v[162:165], v166 offset:8192
	v_add_u32_e32 v130, v229, v179
	v_mfma_f32_32x32x16_bf16 v[82:97], v[146:149], v[134:137], v[82:97]
	ds_read_b128 v[166:169], v166 offset:12288
	v_mfma_f32_32x32x16_bf16 v[66:81], v[150:153], v[134:137], v[66:81]
	ds_read_b128 v[170:173], v174 offset:32768
	v_mfma_f32_32x32x16_bf16 v[50:65], v[146:149], v[138:141], v[50:65]
	ds_read_b128 v[174:177], v174 offset:36864
	v_mfma_f32_32x32x16_bf16 v[34:49], v[150:153], v[138:141], v[34:49]
	v_add_u32_e32 v138, v230, v179
	v_mfma_f32_32x32x16_bf16 v[18:33], v[146:149], v[142:145], v[18:33]
	v_mfma_f32_32x32x16_bf16 v[2:17], v[150:153], v[142:145], v[2:17]
	ds_read_b128 v[150:153], v130
	s_waitcnt lgkmcnt(0)
	v_mfma_f32_32x32x16_bf16 v[114:129], v[170:173], v[154:157], v[114:129]
	ds_read_b128 v[142:145], v130 offset:4096
	v_mfma_f32_32x32x16_bf16 v[98:113], v[174:177], v[154:157], v[98:113]
	ds_read_b128 v[134:137], v130 offset:8192
	v_mfma_f32_32x32x16_bf16 v[82:97], v[170:173], v[158:161], v[82:97]
	ds_read_b128 v[130:133], v130 offset:12288
	v_mfma_f32_32x32x16_bf16 v[66:81], v[174:177], v[158:161], v[66:81]
	ds_read_b128 v[146:149], v138 offset:32768
	v_mfma_f32_32x32x16_bf16 v[50:65], v[170:173], v[162:165], v[50:65]
	ds_read_b128 v[138:141], v138 offset:36864
	s_waitcnt vmcnt(0)
	s_waitcnt vmcnt(0) lgkmcnt(0)
	s_barrier
	v_mfma_f32_32x32x16_bf16 v[34:49], v[174:177], v[162:165], v[34:49]
	v_mfma_f32_32x32x16_bf16 v[18:33], v[170:173], v[166:169], v[18:33]
	v_mfma_f32_32x32x16_bf16 v[2:17], v[174:177], v[166:169], v[2:17]
	s_cmp_eq_u32 s28, s25
	s_cbranch_scc0 .LBB0_246
	v_add_u32_e32 v0, s35, v203
	v_add_u32_e32 v180, s35, v202
	v_add_u32_e32 v162, v0, v228
	v_add_u32_e32 v166, v180, v228
	ds_read_b128 v[154:157], v162
	v_mfma_f32_32x32x16_bf16 v[114:129], v[146:149], v[150:153], v[114:129]
	ds_read_b128 v[158:161], v162 offset:4096
	s_mov_b32 s6, 0x10000
	s_mov_b64 s[40:41], 0x3838900
	s_mov_b64 s[38:39], 0x3858900
	s_mov_b64 s[36:37], 0x27c0080
	v_mfma_f32_32x32x16_bf16 v[98:113], v[138:141], v[150:153], v[98:113]
	ds_read_b128 v[150:153], v162 offset:8192
	v_mfma_f32_32x32x16_bf16 v[82:97], v[146:149], v[142:145], v[82:97]
	ds_read_b128 v[162:165], v162 offset:12288
	v_mfma_f32_32x32x16_bf16 v[66:81], v[138:141], v[142:145], v[66:81]
	ds_read_b128 v[142:145], v166 offset:32768
	v_mfma_f32_32x32x16_bf16 v[50:65], v[146:149], v[134:137], v[50:65]
	ds_read_b128 v[166:169], v166 offset:36864
	v_mfma_f32_32x32x16_bf16 v[34:49], v[138:141], v[134:137], v[34:49]
	v_mfma_f32_32x32x16_bf16 v[18:33], v[146:149], v[130:133], v[18:33]
	v_add_u32_e32 v146, v0, v227
	v_mfma_f32_32x32x16_bf16 v[2:17], v[138:141], v[130:133], v[2:17]
	ds_read_b128 v[130:133], v146
	s_waitcnt lgkmcnt(2)
	v_mfma_f32_32x32x16_bf16 v[114:129], v[142:145], v[154:157], v[114:129]
	ds_read_b128 v[134:137], v146 offset:4096
	s_waitcnt lgkmcnt(2)
	v_mfma_f32_32x32x16_bf16 v[98:113], v[166:169], v[154:157], v[98:113]
	ds_read_b128 v[138:141], v146 offset:8192
	v_mfma_f32_32x32x16_bf16 v[82:97], v[142:145], v[158:161], v[82:97]
	ds_read_b128 v[146:149], v146 offset:12288
	v_mfma_f32_32x32x16_bf16 v[66:81], v[166:169], v[158:161], v[66:81]
	v_add_u32_e32 v158, v180, v227
	ds_read_b128 v[154:157], v158 offset:32768
	v_mfma_f32_32x32x16_bf16 v[50:65], v[142:145], v[150:153], v[50:65]
	ds_read_b128 v[158:161], v158 offset:36864
	v_mfma_f32_32x32x16_bf16 v[34:49], v[166:169], v[150:153], v[34:49]
	v_mfma_f32_32x32x16_bf16 v[2:17], v[166:169], v[162:165], v[2:17]
	v_add_u32_e32 v166, v0, v201
	v_add_u32_e32 v0, v0, v179
	v_mfma_f32_32x32x16_bf16 v[18:33], v[142:145], v[162:165], v[18:33]
	ds_read_b128 v[142:145], v166
	s_waitcnt lgkmcnt(2)
	v_mfma_f32_32x32x16_bf16 v[114:129], v[154:157], v[130:133], v[114:129]
	ds_read_b128 v[150:153], v166 offset:4096
	s_waitcnt lgkmcnt(2)
	v_mfma_f32_32x32x16_bf16 v[98:113], v[158:161], v[130:133], v[98:113]
	v_add_u32_e32 v130, v180, v201
	ds_read_b128 v[162:165], v166 offset:8192
	v_mfma_f32_32x32x16_bf16 v[82:97], v[154:157], v[134:137], v[82:97]
	ds_read_b128 v[166:169], v166 offset:12288
	v_mfma_f32_32x32x16_bf16 v[66:81], v[158:161], v[134:137], v[66:81]
	ds_read_b128 v[170:173], v130 offset:32768
	v_mfma_f32_32x32x16_bf16 v[50:65], v[154:157], v[138:141], v[50:65]
	ds_read_b128 v[174:177], v130 offset:36864
	v_mfma_f32_32x32x16_bf16 v[34:49], v[158:161], v[138:141], v[34:49]
	v_mfma_f32_32x32x16_bf16 v[18:33], v[154:157], v[146:149], v[18:33]
	v_mfma_f32_32x32x16_bf16 v[2:17], v[158:161], v[146:149], v[2:17]
	ds_read_b128 v[146:149], v0
	s_waitcnt lgkmcnt(2)
	v_mfma_f32_32x32x16_bf16 v[114:129], v[170:173], v[142:145], v[114:129]
	ds_read_b128 v[154:157], v0 offset:4096
	s_waitcnt lgkmcnt(2)
	v_mfma_f32_32x32x16_bf16 v[98:113], v[174:177], v[142:145], v[98:113]
	ds_read_b128 v[142:145], v0 offset:8192
	v_mfma_f32_32x32x16_bf16 v[82:97], v[170:173], v[150:153], v[82:97]
	ds_read_b128 v[130:133], v0 offset:12288
	v_add_u32_e32 v0, v180, v179
	v_mov_b32_e32 v179, v1
	v_mfma_f32_32x32x16_bf16 v[66:81], v[174:177], v[150:153], v[66:81]
	ds_read_b128 v[138:141], v0 offset:32768
	v_add_u32_e32 v152, s34, v200
	v_ashrrev_i32_e32 v153, 31, v152
	v_or_b32_e32 v150, s24, v185
	v_lshlrev_b64 v[152:153], 11, v[152:153]
	v_lshl_add_u64 v[152:153], s[14:15], 0, v[152:153]
	v_ashrrev_i32_e32 v151, 31, v150
	v_mfma_f32_32x32x16_bf16 v[50:65], v[170:173], v[162:165], v[50:65]
	ds_read_b128 v[134:137], v0 offset:36864
	v_lshl_add_u64 v[150:151], v[150:151], 1, v[152:153]
	v_lshl_add_u64 v[150:151], v[150:151], 0, v[178:179]
	s_waitcnt vmcnt(0)
	s_waitcnt lgkmcnt(0)
	s_barrier
; template <int EPI>
; DI void phase_gemm(const Params& p, const GemmArgs& ga, char* lds) {
;     ...
;     if (EPI == EPI_M) {
;       u16* mo = ga.Mout + (size_t)(tokbase + pos0 + wm * 128 + r) * DM + n0w + 8 * h;
; #pragma unroll
;       for (int mi = 0; mi < 4; ++mi)
; #pragma unroll
;         for (int ni = 0; ni < 2; ++ni)
; #pragma unroll
;           for (int jp = 0; jp < 2; ++jp) {
;             u32x2 X = {pk_bf16(acc[mi][ni][8 * jp], acc[mi][ni][8 * jp + 1]), pk_bf16(acc[mi][ni][8 * jp + 2], acc[mi][ni][8 * jp + 3])};
;             u32x2 Y = {pk_bf16(acc[mi][ni][8 * jp + 4], acc[mi][ni][8 * jp + 5]), pk_bf16(acc[mi][ni][8 * jp + 6], acc[mi][ni][8 * jp + 7])};
;             half_swap(X, Y);
;             u32x4 v = {X.x, X.y, Y.x, Y.y};
;             *(u32x4*)(mo + (size_t)(mi * 32) * DM + ni * 32 + 16 * jp) = v;
;           }
	v_mfma_f32_32x32x16_bf16 v[34:49], v[174:177], v[162:165], v[34:49]
	v_mfma_f32_32x32x16_bf16 v[18:33], v[170:173], v[166:169], v[18:33]
	v_mfma_f32_32x32x16_bf16 v[2:17], v[174:177], v[166:169], v[2:17]
	v_mfma_f32_32x32x16_bf16 v[82:97], v[138:141], v[154:157], v[82:97]
	v_mfma_f32_32x32x16_bf16 v[50:65], v[138:141], v[142:145], v[50:65]
	s_nop 10
	v_cvt_pk_bf16_f32 v82, v82, v83
	v_cvt_pk_bf16_f32 v83, v84, v85
	v_cvt_pk_bf16_f32 v84, v86, v87
	v_add_co_u32_e32 v86, vcc, s6, v150
	s_mov_b32 s6, 0x30000
	s_nop 0
	v_addc_co_u32_e32 v87, vcc, 0, v151, vcc
	v_mfma_f32_32x32x16_bf16 v[114:129], v[138:141], v[146:149], v[114:129]
	v_cvt_pk_bf16_f32 v50, v50, v51
	v_cvt_pk_bf16_f32 v51, v52, v53
	v_cvt_pk_bf16_f32 v52, v54, v55
	v_add_co_u32_e32 v54, vcc, s84, v150
	v_cvt_pk_bf16_f32 v85, v88, v89
	s_nop 0
	v_addc_co_u32_e32 v55, vcc, 0, v151, vcc
	v_mfma_f32_32x32x16_bf16 v[98:113], v[134:137], v[146:149], v[98:113]
	s_nop 3
	v_cvt_pk_bf16_f32 v114, v114, v115
	v_cvt_pk_bf16_f32 v115, v116, v117
	v_cvt_pk_bf16_f32 v116, v118, v119
	v_cvt_pk_bf16_f32 v117, v120, v121
	v_cvt_pk_bf16_f32 v53, v56, v57
	v_permlane32_swap_b32_e32 v114, v116
	v_mfma_f32_32x32x16_bf16 v[66:81], v[134:137], v[154:157], v[66:81]
	s_nop 0
	v_cvt_pk_bf16_f32 v98, v98, v99
	v_cvt_pk_bf16_f32 v99, v100, v101
	v_cvt_pk_bf16_f32 v100, v102, v103
	v_cvt_pk_bf16_f32 v101, v104, v105
	v_permlane32_swap_b32_e32 v115, v117
	v_permlane32_swap_b32_e32 v98, v100
	v_mfma_f32_32x32x16_bf16 v[34:49], v[134:137], v[142:145], v[34:49]
	s_nop 3
	v_cvt_pk_bf16_f32 v66, v66, v67
	v_cvt_pk_bf16_f32 v67, v68, v69
	v_cvt_pk_bf16_f32 v68, v70, v71
	v_cvt_pk_bf16_f32 v69, v72, v73
	v_permlane32_swap_b32_e32 v99, v101
	v_permlane32_swap_b32_e32 v82, v84
	v_mfma_f32_32x32x16_bf16 v[18:33], v[138:141], v[130:133], v[18:33]
	s_nop 0
	v_cvt_pk_bf16_f32 v34, v34, v35
	v_cvt_pk_bf16_f32 v35, v36, v37
	v_cvt_pk_bf16_f32 v36, v38, v39
	v_cvt_pk_bf16_f32 v37, v40, v41
	v_permlane32_swap_b32_e32 v83, v85
	v_permlane32_swap_b32_e32 v66, v68
	v_mfma_f32_32x32x16_bf16 v[2:17], v[134:137], v[130:133], v[2:17]
	s_nop 3
	v_cvt_pk_bf16_f32 v18, v18, v19
	v_cvt_pk_bf16_f32 v19, v20, v21
	v_cvt_pk_bf16_f32 v20, v22, v23
	v_cvt_pk_bf16_f32 v21, v24, v25
	v_add_co_u32_e32 v22, vcc, s6, v150
	v_permlane32_swap_b32_e32 v67, v69
	s_nop 1
	v_cvt_pk_bf16_f32 v2, v2, v3
	v_cvt_pk_bf16_f32 v3, v4, v5
	v_cvt_pk_bf16_f32 v4, v6, v7
	v_cvt_pk_bf16_f32 v5, v8, v9
	v_permlane32_swap_b32_e32 v50, v52
	v_permlane32_swap_b32_e32 v51, v53
	v_permlane32_swap_b32_e32 v34, v36
	v_permlane32_swap_b32_e32 v35, v37
	v_permlane32_swap_b32_e32 v18, v20
	v_permlane32_swap_b32_e32 v19, v21
	v_addc_co_u32_e32 v23, vcc, 0, v151, vcc
	v_permlane32_swap_b32_e32 v2, v4
	v_permlane32_swap_b32_e32 v3, v5
	global_store_dwordx4 v[150:151], v[114:117], off
	global_store_dwordx4 v[150:151], v[98:101], off offset:64
	global_store_dwordx4 v[86:87], v[82:85], off
	v_cvt_pk_bf16_f32 v114, v122, v123
	v_cvt_pk_bf16_f32 v115, v124, v125
	v_cvt_pk_bf16_f32 v116, v126, v127
	v_cvt_pk_bf16_f32 v117, v128, v129
	v_cvt_pk_bf16_f32 v98, v106, v107
	v_cvt_pk_bf16_f32 v99, v108, v109
	v_cvt_pk_bf16_f32 v100, v110, v111
	v_cvt_pk_bf16_f32 v101, v112, v113
	v_cvt_pk_bf16_f32 v82, v90, v91
	v_cvt_pk_bf16_f32 v83, v92, v93
	v_cvt_pk_bf16_f32 v84, v94, v95
	v_cvt_pk_bf16_f32 v85, v96, v97
	global_store_dwordx4 v[86:87], v[66:69], off offset:64
	global_store_dwordx4 v[54:55], v[50:53], off
	global_store_dwordx4 v[54:55], v[34:37], off offset:64
	v_cvt_pk_bf16_f32 v66, v74, v75
	v_cvt_pk_bf16_f32 v67, v76, v77
	v_cvt_pk_bf16_f32 v68, v78, v79
	v_cvt_pk_bf16_f32 v69, v80, v81
	v_cvt_pk_bf16_f32 v50, v58, v59
	v_cvt_pk_bf16_f32 v51, v60, v61
	v_cvt_pk_bf16_f32 v52, v62, v63
	v_cvt_pk_bf16_f32 v53, v64, v65
	v_cvt_pk_bf16_f32 v34, v42, v43
	v_cvt_pk_bf16_f32 v35, v44, v45
	v_cvt_pk_bf16_f32 v36, v46, v47
	v_cvt_pk_bf16_f32 v37, v48, v49
	global_store_dwordx4 v[22:23], v[18:21], off
	global_store_dwordx4 v[22:23], v[2:5], off offset:64
	v_permlane32_swap_b32_e32 v114, v116
	v_cvt_pk_bf16_f32 v18, v26, v27
	v_cvt_pk_bf16_f32 v19, v28, v29
	v_cvt_pk_bf16_f32 v20, v30, v31
	v_cvt_pk_bf16_f32 v21, v32, v33
	v_cvt_pk_bf16_f32 v2, v10, v11
	v_cvt_pk_bf16_f32 v3, v12, v13
	v_cvt_pk_bf16_f32 v4, v14, v15
	v_cvt_pk_bf16_f32 v5, v16, v17
	v_permlane32_swap_b32_e32 v115, v117
	v_permlane32_swap_b32_e32 v98, v100
	v_permlane32_swap_b32_e32 v99, v101
	v_permlane32_swap_b32_e32 v82, v84
	v_permlane32_swap_b32_e32 v83, v85
	v_permlane32_swap_b32_e32 v66, v68
	v_permlane32_swap_b32_e32 v67, v69
	v_permlane32_swap_b32_e32 v50, v52
	v_permlane32_swap_b32_e32 v51, v53
	v_permlane32_swap_b32_e32 v34, v36
	v_permlane32_swap_b32_e32 v35, v37
	v_permlane32_swap_b32_e32 v18, v20
	v_permlane32_swap_b32_e32 v19, v21
	v_permlane32_swap_b32_e32 v2, v4
	v_permlane32_swap_b32_e32 v3, v5
	global_store_dwordx4 v[150:151], v[114:117], off offset:32
	global_store_dwordx4 v[150:151], v[98:101], off offset:96
	global_store_dwordx4 v[86:87], v[82:85], off offset:32
	global_store_dwordx4 v[86:87], v[66:69], off offset:96
	global_store_dwordx4 v[54:55], v[50:53], off offset:32
	global_store_dwordx4 v[54:55], v[34:37], off offset:96
	global_store_dwordx4 v[22:23], v[18:21], off offset:32
	global_store_dwordx4 v[22:23], v[2:5], off offset:96
	s_branch .LBB0_243

; DI void flash_pass_q2(f32x16 (&o)[2][2], const u16* __restrict__ Qp0, const u16* __restrict__ Qp1,
;                       const u16* __restrict__ Kb, int ldk, const u16* __restrict__ Vt, int S, int ntiles, char* lds) {
;     ...
;     const char* st = lds + (ti & 1) * ATT_STAGE;
;     f32x16 s[2][2];
; #pragma unroll
;     for (int hq = 0; hq < 2; ++hq)
; #pragma unroll
;       for (int kb = 0; kb < 2; ++kb)
; #pragma unroll
;         for (int i = 0; i < 16; ++i) s[hq][kb][i] = 0.f;
;     {
;       bf16x8 ka[4], kb_[4];
; #pragma unroll
;       for (int ks = 0; ks < 4; ++ks) {
;         const int co = ((2 * ks + h) ^ ksw) << 4;
;         ka[ks] = *(const bf16x8*)(st + pr * 128 + co);
;         kb_[ks] = *(const bf16x8*)(st + (32 + pr) * 128 + co);
;       }
;       asm volatile("" ::: "memory");
; #pragma unroll
;       for (int ks = 0; ks < 4; ++ks) {
;         s[0][0] = MFMA(ka[ks], q[0][ks], s[0][0]);
;         s[0][1] = MFMA(kb_[ks], q[0][ks], s[0][1]);
;         s[1][0] = MFMA(ka[ks], q[1][ks], s[1][0]);
;         s[1][1] = MFMA(kb_[ks], q[1][ks], s[1][1]);
;       }
;     }
;     bf16x8 pf[2][2][2];
; #pragma unroll
;     for (int hq = 0; hq < 2; ++hq) {
;       float t[32];
; #pragma unroll
;       for (int i = 0; i < 16; ++i) { t[i] = s[hq][0][i]; t[16 + i] = s[hq][1][i]; }
;       float mx = t[0];
; #pragma unroll
;       for (int e = 1; e < 32; ++e) mx = fmaxf(mx, t[e]);
;       mx = fmaxf(mx, __shfl_xor(mx, 32));
;       if (__builtin_amdgcn_ballot_w64(mx > m_run[hq] + 8.f) != 0ull) {
;         const float m_new = fmaxf(m_run[hq], mx);
;         const float alpha = fexp2(m_run[hq] - m_new);
;         l_run[hq] *= alpha;
;         m_run[hq] = m_new;
; #pragma unroll
;         for (int mv = 0; mv < 2; ++mv)
; #pragma unroll
;           for (int i = 0; i < 16; ++i) o[hq][mv][i] *= alpha;
;       }
;       float ls = 0.f;
; #pragma unroll
;       for (int e = 0; e < 32; ++e) { t[e] = fexp2(t[e] - m_run[hq]); ls += t[e]; }
;       l_run[hq] += ls;
; #pragma unroll
;       for (int kb = 0; kb < 2; ++kb)
; #pragma unroll
;         for (int c2 = 0; c2 < 2; ++c2) {
;           const int e0 = kb * 16 + c2 * 8;
;           u32x4 pw = {pk_bf16(t[e0], t[e0 + 1]), pk_bf16(t[e0 + 2], t[e0 + 3]), pk_bf16(t[e0 + 4], t[e0 + 5]), pk_bf16(t[e0 + 6], t[e0 + 7])};
;           pf[hq][kb][c2] = __builtin_bit_cast(bf16x8, pw);
;         }
.LBB0_280:
	s_and_b32 s29, 1, s22
	s_cselect_b32 s23, 0x6000, 0
	s_cselect_b32 s21, 0, 0x6000
	s_add_i32 s22, s22, 1
	v_add_u32_e32 v11, s21, v238
	v_add_u32_e32 v248, s21, v195
	v_add_u32_e32 v249, v11, v239
	ds_read_b128 v[2:5], v249
	ds_read_b128 v[6:9], v249 offset:4096
	v_add_u32_e32 v249, v11, v236
	ds_read_b128 v[12:15], v249
	ds_read_b128 v[240:243], v249 offset:4096
	v_add_u32_e32 v249, s23, v237
	v_cmp_lt_u32_e32 vcc, s22, v185
	s_waitcnt vmcnt(1)
	ds_write_b128 v249, v[176:179]
	s_waitcnt vmcnt(0)
	ds_write_b128 v249, v[180:183] offset:8192
	s_and_saveexec_b64 s[20:21], vcc
	s_cbranch_execz .Lg2_noload
	global_load_dwordx4 v[176:179], v[202:203], off
	global_load_dwordx4 v[180:183], v[200:201], off
	v_lshl_add_u64 v[200:201], v[200:201], 0, s[4:5]
	v_lshl_add_u64 v[202:203], v[202:203], 0, s[82:83]
.Lg2_noload:
	s_or_b64 exec, exec, s[20:21]
	v_cmp_eq_u32_e32 vcc, s22, v185
	s_waitcnt lgkmcnt(5)
	v_mfma_f32_32x32x16_bf16 v[128:143], v[2:5], v[168:171], 0
	s_waitcnt lgkmcnt(4)
	v_mfma_f32_32x32x16_bf16 v[112:127], v[6:9], v[168:171], 0
	v_mfma_f32_32x32x16_bf16 v[96:111], v[2:5], v[172:175], 0
	v_mfma_f32_32x32x16_bf16 v[80:95], v[6:9], v[172:175], 0
	s_or_b64 s[18:19], vcc, s[18:19]
	v_add_u32_e32 v249, v11, v235
	ds_read_b128 v[2:5], v249
	ds_read_b128 v[6:9], v249 offset:4096
	s_waitcnt lgkmcnt(5)
	v_mfma_f32_32x32x16_bf16 v[128:143], v[12:15], v[164:167], v[128:143]
	s_waitcnt lgkmcnt(4)
	v_mfma_f32_32x32x16_bf16 v[112:127], v[240:243], v[164:167], v[112:127]
	v_mfma_f32_32x32x16_bf16 v[96:111], v[12:15], v[160:163], v[96:111]
	v_mfma_f32_32x32x16_bf16 v[80:95], v[240:243], v[160:163], v[80:95]
	v_add_u32_e32 v249, v11, v234
	ds_read_b128 v[12:15], v249
	ds_read_b128 v[240:243], v249 offset:4096
	s_waitcnt lgkmcnt(3)
	v_mfma_f32_32x32x16_bf16 v[128:143], v[2:5], v[156:159], v[128:143]
	s_waitcnt lgkmcnt(2)
	v_mfma_f32_32x32x16_bf16 v[112:127], v[6:9], v[156:159], v[112:127]
	v_mfma_f32_32x32x16_bf16 v[96:111], v[2:5], v[152:155], v[96:111]
	v_mfma_f32_32x32x16_bf16 v[80:95], v[6:9], v[152:155], v[80:95]
	v_add_u32_e32 v249, v248, v232
	ds_read_b128 v[2:5], v249 offset:8192
	ds_read_b128 v[6:9], v249 offset:12288
	s_waitcnt lgkmcnt(3)
	v_mfma_f32_32x32x16_bf16 v[128:143], v[12:15], v[148:151], v[128:143]
	s_waitcnt lgkmcnt(2)
	v_mfma_f32_32x32x16_bf16 v[112:127], v[240:243], v[148:151], v[112:127]
	v_mfma_f32_32x32x16_bf16 v[96:111], v[12:15], v[144:147], v[96:111]
	v_mfma_f32_32x32x16_bf16 v[80:95], v[240:243], v[144:147], v[80:95]
	v_add_u32_e32 v249, v248, v231
	ds_read_b128 v[12:15], v249 offset:8192
	ds_read_b128 v[240:243], v249 offset:12288
.Lg2_sm0:
	s_nop 4
	v_sub_f32_e32 v128, v128, v10
	v_sub_f32_e32 v129, v129, v10
	v_sub_f32_e32 v130, v130, v10
	v_sub_f32_e32 v131, v131, v10
	v_sub_f32_e32 v132, v132, v10
	v_sub_f32_e32 v133, v133, v10
	v_sub_f32_e32 v134, v134, v10
	v_sub_f32_e32 v135, v135, v10
	v_sub_f32_e32 v136, v136, v10
	v_sub_f32_e32 v137, v137, v10
	v_sub_f32_e32 v138, v138, v10
	v_sub_f32_e32 v139, v139, v10
	v_sub_f32_e32 v140, v140, v10
	v_sub_f32_e32 v141, v141, v10
	v_sub_f32_e32 v142, v142, v10
	v_sub_f32_e32 v143, v143, v10
	v_sub_f32_e32 v112, v112, v10
	v_sub_f32_e32 v113, v113, v10
	v_sub_f32_e32 v114, v114, v10
	v_sub_f32_e32 v115, v115, v10
	v_sub_f32_e32 v116, v116, v10
	v_sub_f32_e32 v117, v117, v10
	v_sub_f32_e32 v118, v118, v10
	v_sub_f32_e32 v119, v119, v10
	v_sub_f32_e32 v120, v120, v10
	v_sub_f32_e32 v121, v121, v10
	v_sub_f32_e32 v122, v122, v10
	v_sub_f32_e32 v123, v123, v10
	v_sub_f32_e32 v124, v124, v10
	v_sub_f32_e32 v125, v125, v10
	v_sub_f32_e32 v126, v126, v10
	v_sub_f32_e32 v127, v127, v10
	v_exp_f32_e32 v128, v128
	v_exp_f32_e32 v129, v129
	v_exp_f32_e32 v130, v130
	v_exp_f32_e32 v131, v131
	v_exp_f32_e32 v132, v132
	v_exp_f32_e32 v133, v133
	v_exp_f32_e32 v134, v134
	v_exp_f32_e32 v135, v135
	v_exp_f32_e32 v136, v136
	v_exp_f32_e32 v137, v137
	v_add_f32_e32 v210, v128, v130
	v_add_f32_e32 v246, v129, v131
	v_exp_f32_e32 v138, v138
	v_exp_f32_e32 v139, v139
	v_add_f32_e32 v210, v210, v132
	v_add_f32_e32 v246, v246, v133
	v_exp_f32_e32 v140, v140
	v_exp_f32_e32 v141, v141
	v_add_f32_e32 v210, v210, v134
	v_add_f32_e32 v246, v246, v135
	v_exp_f32_e32 v142, v142
	v_exp_f32_e32 v143, v143
	v_add_f32_e32 v210, v210, v136
	v_add_f32_e32 v246, v246, v137
	v_exp_f32_e32 v112, v112
	v_exp_f32_e32 v113, v113
	v_add_f32_e32 v210, v210, v138
	v_add_f32_e32 v246, v246, v139
	v_exp_f32_e32 v114, v114
	v_exp_f32_e32 v115, v115
	v_add_f32_e32 v210, v210, v140
	v_add_f32_e32 v246, v246, v141
	v_exp_f32_e32 v116, v116
	v_exp_f32_e32 v117, v117
	v_add_f32_e32 v210, v210, v142
	v_add_f32_e32 v246, v246, v143
	v_exp_f32_e32 v118, v118
	v_exp_f32_e32 v119, v119
	v_add_f32_e32 v210, v210, v112
	v_add_f32_e32 v246, v246, v113
	v_exp_f32_e32 v120, v120
	v_exp_f32_e32 v121, v121
	v_add_f32_e32 v210, v210, v114
	v_add_f32_e32 v246, v246, v115
	v_exp_f32_e32 v122, v122
	v_exp_f32_e32 v123, v123
	v_add_f32_e32 v210, v210, v116
	v_add_f32_e32 v246, v246, v117
	v_exp_f32_e32 v124, v124
	v_exp_f32_e32 v125, v125
	v_add_f32_e32 v210, v210, v118
	v_add_f32_e32 v246, v246, v119
	v_exp_f32_e32 v126, v126
	v_exp_f32_e32 v127, v127
	v_add_f32_e32 v210, v210, v120
	v_add_f32_e32 v246, v246, v121
	v_add_f32_e32 v210, v210, v122
	v_add_f32_e32 v246, v246, v123
	v_add_f32_e32 v210, v210, v124
	v_add_f32_e32 v246, v246, v125
	v_add_f32_e32 v210, v210, v126
	v_add_f32_e32 v246, v246, v127
	v_add_f32_e32 v210, v210, v246
	v_cmp_lt_f32_e32 vcc, 0x5d800000, v210
	s_cbranch_vccnz .Lg2_fix0
	v_add_f32_e32 v0, v0, v210
	v_cvt_pk_bf16_f32 v128, v128, v129
	v_cvt_pk_bf16_f32 v129, v130, v131
	v_cvt_pk_bf16_f32 v130, v132, v133
	v_cvt_pk_bf16_f32 v131, v134, v135
	v_cvt_pk_bf16_f32 v136, v136, v137
	v_cvt_pk_bf16_f32 v137, v138, v139
	v_cvt_pk_bf16_f32 v138, v140, v141
	v_cvt_pk_bf16_f32 v139, v142, v143
	v_cvt_pk_bf16_f32 v112, v112, v113
	v_cvt_pk_bf16_f32 v113, v114, v115
	v_cvt_pk_bf16_f32 v114, v116, v117
	v_cvt_pk_bf16_f32 v115, v118, v119
	v_cvt_pk_bf16_f32 v120, v120, v121
	v_cvt_pk_bf16_f32 v121, v122, v123
	v_cvt_pk_bf16_f32 v122, v124, v125
	v_cvt_pk_bf16_f32 v123, v126, v127
	s_waitcnt lgkmcnt(3)
	v_mfma_f32_32x32x16_bf16 v[64:79], v[2:5], v[128:131], v[64:79]
	s_waitcnt lgkmcnt(2)
	v_mfma_f32_32x32x16_bf16 v[48:63], v[6:9], v[128:131], v[48:63]
	s_waitcnt lgkmcnt(1)
	v_mfma_f32_32x32x16_bf16 v[64:79], v[12:15], v[136:139], v[64:79]
	s_waitcnt lgkmcnt(0)
	v_mfma_f32_32x32x16_bf16 v[48:63], v[240:243], v[136:139], v[48:63]
; #define MFMA(a, b, c) __builtin_amdgcn_mfma_f32_32x32x16_bf16((a), (b), (c), 0, 0, 0)
; DI float fexp2(float x) { return __builtin_amdgcn_exp2f(x); }
; DI void flash_pass_q2(f32x16 (&o)[2][2], const u16* __restrict__ Qp0, const u16* __restrict__ Qp1,
;                       const u16* __restrict__ Kb, int ldk, const u16* __restrict__ Vt, int S, int ntiles, char* lds) {
;     ...
;     for (int hq = 0; hq < 2; ++hq) {
;       float t[32];
; #pragma unroll
;       for (int i = 0; i < 16; ++i) { t[i] = s[hq][0][i]; t[16 + i] = s[hq][1][i]; }
;       float mx = t[0];
; #pragma unroll
;       for (int e = 1; e < 32; ++e) mx = fmaxf(mx, t[e]);
;       mx = fmaxf(mx, __shfl_xor(mx, 32));
;       if (__builtin_amdgcn_ballot_w64(mx > m_run[hq] + 8.f) != 0ull) {
;         const float m_new = fmaxf(m_run[hq], mx);
;         const float alpha = fexp2(m_run[hq] - m_new);
;         l_run[hq] *= alpha;
;         m_run[hq] = m_new;
; #pragma unroll
;         for (int mv = 0; mv < 2; ++mv)
; #pragma unroll
;           for (int i = 0; i < 16; ++i) o[hq][mv][i] *= alpha;
;       }
;       float ls = 0.f;
; #pragma unroll
;       for (int e = 0; e < 32; ++e) { t[e] = fexp2(t[e] - m_run[hq]); ls += t[e]; }
;       l_run[hq] += ls;
; #pragma unroll
;       for (int kb = 0; kb < 2; ++kb)
; #pragma unroll
;         for (int c2 = 0; c2 < 2; ++c2) {
;           const int e0 = kb * 16 + c2 * 8;
;           u32x4 pw = {pk_bf16(t[e0], t[e0 + 1]), pk_bf16(t[e0 + 2], t[e0 + 3]), pk_bf16(t[e0 + 4], t[e0 + 5]), pk_bf16(t[e0 + 6], t[e0 + 7])};
;           pf[hq][kb][c2] = __builtin_bit_cast(bf16x8, pw);
;         }
;     }
;     bf16x8 vf[2][2][2];
; #pragma unroll
;     for (int kb = 0; kb < 2; ++kb)
; #pragma unroll
;       for (int c2 = 0; c2 < 2; ++c2) {
;         const int co = ((4 * kb + 2 * c2 + h) ^ vsw) << 4;
; #pragma unroll
;         for (int mv = 0; mv < 2; ++mv) vf[kb][c2][mv] = *(const bf16x8*)(st + 8192 + (mv * 32 + r) * 128 + co);
;       }
;     asm volatile("" ::: "memory");
; #pragma unroll
;     for (int kb = 0; kb < 2; ++kb)
; #pragma unroll
;       for (int c2 = 0; c2 < 2; ++c2)
; #pragma unroll
;         for (int mv = 0; mv < 2; ++mv) {
;           o[0][mv] = MFMA(vf[kb][c2][mv], pf[0][kb][c2], o[0][mv]);
;           o[1][mv] = MFMA(vf[kb][c2][mv], pf[1][kb][c2], o[1][mv]);
;         }
;     __syncthreads();
;   }
.Lg2_sm1:
	v_sub_f32_e32 v96, v96, v233
	v_sub_f32_e32 v97, v97, v233
	v_sub_f32_e32 v98, v98, v233
	v_sub_f32_e32 v99, v99, v233
	v_sub_f32_e32 v100, v100, v233
	v_sub_f32_e32 v101, v101, v233
	v_sub_f32_e32 v102, v102, v233
	v_sub_f32_e32 v103, v103, v233
	v_sub_f32_e32 v104, v104, v233
	v_sub_f32_e32 v105, v105, v233
	v_sub_f32_e32 v106, v106, v233
	v_sub_f32_e32 v107, v107, v233
	v_sub_f32_e32 v108, v108, v233
	v_sub_f32_e32 v109, v109, v233
	v_sub_f32_e32 v110, v110, v233
	v_sub_f32_e32 v111, v111, v233
	v_sub_f32_e32 v80, v80, v233
	v_sub_f32_e32 v81, v81, v233
	v_sub_f32_e32 v82, v82, v233
	v_sub_f32_e32 v83, v83, v233
	v_sub_f32_e32 v84, v84, v233
	v_sub_f32_e32 v85, v85, v233
	v_sub_f32_e32 v86, v86, v233
	v_sub_f32_e32 v87, v87, v233
	v_sub_f32_e32 v88, v88, v233
	v_sub_f32_e32 v89, v89, v233
	v_sub_f32_e32 v90, v90, v233
	v_sub_f32_e32 v91, v91, v233
	v_sub_f32_e32 v92, v92, v233
	v_sub_f32_e32 v93, v93, v233
	v_sub_f32_e32 v94, v94, v233
	v_sub_f32_e32 v95, v95, v233
	v_exp_f32_e32 v96, v96
	v_exp_f32_e32 v97, v97
	v_exp_f32_e32 v98, v98
	v_exp_f32_e32 v99, v99
	v_exp_f32_e32 v100, v100
	v_exp_f32_e32 v101, v101
	v_exp_f32_e32 v102, v102
	v_exp_f32_e32 v103, v103
	v_exp_f32_e32 v104, v104
	v_exp_f32_e32 v105, v105
	v_add_f32_e32 v210, v96, v98
	v_add_f32_e32 v246, v97, v99
	v_exp_f32_e32 v106, v106
	v_exp_f32_e32 v107, v107
	v_add_f32_e32 v210, v210, v100
	v_add_f32_e32 v246, v246, v101
	v_exp_f32_e32 v108, v108
	v_exp_f32_e32 v109, v109
	v_add_f32_e32 v210, v210, v102
	v_add_f32_e32 v246, v246, v103
	v_exp_f32_e32 v110, v110
	v_exp_f32_e32 v111, v111
	v_add_f32_e32 v210, v210, v104
	v_add_f32_e32 v246, v246, v105
	v_exp_f32_e32 v80, v80
	v_exp_f32_e32 v81, v81
	v_add_f32_e32 v210, v210, v106
	v_add_f32_e32 v246, v246, v107
	v_exp_f32_e32 v82, v82
	v_exp_f32_e32 v83, v83
	v_add_f32_e32 v210, v210, v108
	v_add_f32_e32 v246, v246, v109
	v_exp_f32_e32 v84, v84
	v_exp_f32_e32 v85, v85
	v_add_f32_e32 v210, v210, v110
	v_add_f32_e32 v246, v246, v111
	v_exp_f32_e32 v86, v86
	v_exp_f32_e32 v87, v87
	v_add_f32_e32 v210, v210, v80
	v_add_f32_e32 v246, v246, v81
	v_exp_f32_e32 v88, v88
	v_exp_f32_e32 v89, v89
	v_add_f32_e32 v210, v210, v82
	v_add_f32_e32 v246, v246, v83
	v_exp_f32_e32 v90, v90
	v_exp_f32_e32 v91, v91
	v_add_f32_e32 v210, v210, v84
	v_add_f32_e32 v246, v246, v85
	v_exp_f32_e32 v92, v92
	v_exp_f32_e32 v93, v93
	v_add_f32_e32 v210, v210, v86
	v_add_f32_e32 v246, v246, v87
	v_exp_f32_e32 v94, v94
	v_exp_f32_e32 v95, v95
	v_add_f32_e32 v210, v210, v88
	v_add_f32_e32 v246, v246, v89
	v_add_f32_e32 v210, v210, v90
	v_add_f32_e32 v246, v246, v91
	v_add_f32_e32 v210, v210, v92
	v_add_f32_e32 v246, v246, v93
	v_add_f32_e32 v210, v210, v94
	v_add_f32_e32 v246, v246, v95
	v_add_f32_e32 v210, v210, v246
	v_cmp_lt_f32_e32 vcc, 0x5d800000, v210
	s_cbranch_vccnz .Lg2_fix1
	v_add_f32_e32 v229, v229, v210
	v_cvt_pk_bf16_f32 v96, v96, v97
	v_cvt_pk_bf16_f32 v97, v98, v99
	v_cvt_pk_bf16_f32 v98, v100, v101
	v_cvt_pk_bf16_f32 v99, v102, v103
	v_cvt_pk_bf16_f32 v104, v104, v105
	v_cvt_pk_bf16_f32 v105, v106, v107
	v_cvt_pk_bf16_f32 v106, v108, v109
	v_cvt_pk_bf16_f32 v107, v110, v111
	v_cvt_pk_bf16_f32 v80, v80, v81
	v_cvt_pk_bf16_f32 v81, v82, v83
	v_cvt_pk_bf16_f32 v82, v84, v85
	v_cvt_pk_bf16_f32 v83, v86, v87
	v_cvt_pk_bf16_f32 v88, v88, v89
	v_cvt_pk_bf16_f32 v89, v90, v91
	v_cvt_pk_bf16_f32 v90, v92, v93
	v_cvt_pk_bf16_f32 v91, v94, v95
	v_mfma_f32_32x32x16_bf16 v[32:47], v[2:5], v[96:99], v[32:47]
	v_mfma_f32_32x32x16_bf16 v[16:31], v[6:9], v[96:99], v[16:31]
	v_add_u32_e32 v249, v248, v230
	ds_read_b128 v[2:5], v249 offset:8192
	ds_read_b128 v[6:9], v249 offset:12288
	v_mfma_f32_32x32x16_bf16 v[32:47], v[12:15], v[104:107], v[32:47]
	v_mfma_f32_32x32x16_bf16 v[16:31], v[240:243], v[104:107], v[16:31]
	v_add_u32_e32 v249, v248, v228
	ds_read_b128 v[12:15], v249 offset:8192
	ds_read_b128 v[240:243], v249 offset:12288
	s_waitcnt lgkmcnt(3)
	v_mfma_f32_32x32x16_bf16 v[64:79], v[2:5], v[112:115], v[64:79]
	s_waitcnt lgkmcnt(2)
	v_mfma_f32_32x32x16_bf16 v[48:63], v[6:9], v[112:115], v[48:63]
	v_mfma_f32_32x32x16_bf16 v[32:47], v[2:5], v[80:83], v[32:47]
	v_mfma_f32_32x32x16_bf16 v[16:31], v[6:9], v[80:83], v[16:31]
	s_waitcnt lgkmcnt(1)
	v_mfma_f32_32x32x16_bf16 v[64:79], v[12:15], v[120:123], v[64:79]
	s_waitcnt lgkmcnt(0)
	v_mfma_f32_32x32x16_bf16 v[48:63], v[240:243], v[120:123], v[48:63]
	v_mfma_f32_32x32x16_bf16 v[32:47], v[12:15], v[88:91], v[32:47]
	v_mfma_f32_32x32x16_bf16 v[16:31], v[240:243], v[88:91], v[16:31]
	v_mov_b32_e32 v14, s23
	s_waitcnt lgkmcnt(0)
	s_barrier
	s_andn2_b64 exec, exec, s[18:19]
	s_cbranch_execnz .LBB0_280
	s_branch .LBB0_286
; DI float fexp2(float x) { return __builtin_amdgcn_exp2f(x); }
; DI void flash_pass_q2(f32x16 (&o)[2][2], const u16* __restrict__ Qp0, const u16* __restrict__ Qp1,
;                       const u16* __restrict__ Kb, int ldk, const u16* __restrict__ Vt, int S, int ntiles, char* lds) {
;     ...
;       float mx = t[0];
; #pragma unroll
;       for (int e = 1; e < 32; ++e) mx = fmaxf(mx, t[e]);
;       mx = fmaxf(mx, __shfl_xor(mx, 32));
;       if (__builtin_amdgcn_ballot_w64(mx > m_run[hq] + 8.f) != 0ull) {
;         const float m_new = fmaxf(m_run[hq], mx);
;         const float alpha = fexp2(m_run[hq] - m_new);
;         l_run[hq] *= alpha;
;         m_run[hq] = m_new;
; #pragma unroll
;         for (int mv = 0; mv < 2; ++mv)
; #pragma unroll
;           for (int i = 0; i < 16; ++i) o[hq][mv][i] *= alpha;
;       }
.Lg2_fix0:
	s_waitcnt lgkmcnt(0)
	s_xor_b32 s29, s23, 0x6000
	v_add_u32_e32 v11, s29, v238
	v_add_u32_e32 v249, v11, v239
	ds_read_b128 v[2:5], v249
	ds_read_b128 v[6:9], v249 offset:4096
	v_add_u32_e32 v249, v11, v236
	ds_read_b128 v[12:15], v249
	ds_read_b128 v[240:243], v249 offset:4096
	s_waitcnt lgkmcnt(3)
	v_mfma_f32_32x32x16_bf16 v[128:143], v[2:5], v[168:171], 0
	s_waitcnt lgkmcnt(2)
	v_mfma_f32_32x32x16_bf16 v[112:127], v[6:9], v[168:171], 0
	v_add_u32_e32 v249, v11, v235
	ds_read_b128 v[2:5], v249
	ds_read_b128 v[6:9], v249 offset:4096
	s_waitcnt lgkmcnt(3)
	v_mfma_f32_32x32x16_bf16 v[128:143], v[12:15], v[164:167], v[128:143]
	s_waitcnt lgkmcnt(2)
	v_mfma_f32_32x32x16_bf16 v[112:127], v[240:243], v[164:167], v[112:127]
	v_add_u32_e32 v249, v11, v234
	ds_read_b128 v[12:15], v249
	ds_read_b128 v[240:243], v249 offset:4096
	s_waitcnt lgkmcnt(3)
	v_mfma_f32_32x32x16_bf16 v[128:143], v[2:5], v[156:159], v[128:143]
	s_waitcnt lgkmcnt(2)
	v_mfma_f32_32x32x16_bf16 v[112:127], v[6:9], v[156:159], v[112:127]
	s_waitcnt lgkmcnt(1)
	v_mfma_f32_32x32x16_bf16 v[128:143], v[12:15], v[148:151], v[128:143]
	s_waitcnt lgkmcnt(0)
	v_mfma_f32_32x32x16_bf16 v[112:127], v[240:243], v[148:151], v[112:127]
	v_add_u32_e32 v249, v248, v232
	ds_read_b128 v[2:5], v249 offset:8192
	ds_read_b128 v[6:9], v249 offset:12288
	v_add_u32_e32 v249, v248, v231
	ds_read_b128 v[12:15], v249 offset:8192
	ds_read_b128 v[240:243], v249 offset:12288
	s_nop 3
	v_max3_f32 v244, v128, v129, v130
	v_max3_f32 v245, v139, v140, v141
	v_max3_f32 v247, v118, v119, v120
	v_max3_f32 v244, v244, v131, v132
	v_max3_f32 v245, v245, v142, v143
	v_max3_f32 v247, v247, v121, v122
	v_max3_f32 v244, v244, v133, v134
	v_max3_f32 v245, v245, v112, v113
	v_max3_f32 v247, v247, v123, v124
	v_max3_f32 v244, v244, v135, v136
	v_max3_f32 v245, v245, v114, v115
	v_max3_f32 v247, v247, v125, v126
	v_max3_f32 v244, v244, v137, v138
	v_max3_f32 v245, v245, v116, v117
	v_max_f32_e32 v247, v247, v127
	v_max3_f32 v244, v244, v245, v247
	v_mov_b32_e32 v245, v244
	v_max_f32_e32 v247, v10, v10
	s_nop 0
	v_permlane32_swap_b32_e32 v244, v245
	v_max3_f32 v245, v244, v245, v247
	v_sub_f32_e32 v247, v10, v245
	v_exp_f32_e32 v247, v247
	v_mov_b32_e32 v10, v245
	v_mov_b32_e32 v244, v247
	v_mul_f32_e32 v0, v0, v244
	v_pk_mul_f32 v[64:65], v[64:65], v[244:245] op_sel_hi:[1,0]
	v_pk_mul_f32 v[66:67], v[66:67], v[244:245] op_sel_hi:[1,0]
	v_pk_mul_f32 v[68:69], v[68:69], v[244:245] op_sel_hi:[1,0]
	v_pk_mul_f32 v[70:71], v[70:71], v[244:245] op_sel_hi:[1,0]
	v_pk_mul_f32 v[72:73], v[72:73], v[244:245] op_sel_hi:[1,0]
	v_pk_mul_f32 v[74:75], v[74:75], v[244:245] op_sel_hi:[1,0]
	v_pk_mul_f32 v[76:77], v[76:77], v[244:245] op_sel_hi:[1,0]
	v_pk_mul_f32 v[78:79], v[78:79], v[244:245] op_sel_hi:[1,0]
	v_pk_mul_f32 v[48:49], v[48:49], v[244:245] op_sel_hi:[1,0]
	v_pk_mul_f32 v[50:51], v[50:51], v[244:245] op_sel_hi:[1,0]
	v_pk_mul_f32 v[52:53], v[52:53], v[244:245] op_sel_hi:[1,0]
	v_pk_mul_f32 v[54:55], v[54:55], v[244:245] op_sel_hi:[1,0]
	v_pk_mul_f32 v[56:57], v[56:57], v[244:245] op_sel_hi:[1,0]
	v_pk_mul_f32 v[58:59], v[58:59], v[244:245] op_sel_hi:[1,0]
	v_pk_mul_f32 v[60:61], v[60:61], v[244:245] op_sel_hi:[1,0]
	v_pk_mul_f32 v[62:63], v[62:63], v[244:245] op_sel_hi:[1,0]
	s_branch .Lg2_sm0
.Lg2_fix1:
	s_waitcnt lgkmcnt(0)
	s_xor_b32 s29, s23, 0x6000
	v_add_u32_e32 v11, s29, v238
	v_add_u32_e32 v249, v11, v239
	ds_read_b128 v[2:5], v249
	ds_read_b128 v[6:9], v249 offset:4096
	v_add_u32_e32 v249, v11, v236
	ds_read_b128 v[12:15], v249
	ds_read_b128 v[240:243], v249 offset:4096
	s_waitcnt lgkmcnt(3)
	v_mfma_f32_32x32x16_bf16 v[96:111], v[2:5], v[172:175], 0
	s_waitcnt lgkmcnt(2)
	v_mfma_f32_32x32x16_bf16 v[80:95], v[6:9], v[172:175], 0
	v_add_u32_e32 v249, v11, v235
	ds_read_b128 v[2:5], v249
	ds_read_b128 v[6:9], v249 offset:4096
	s_waitcnt lgkmcnt(3)
	v_mfma_f32_32x32x16_bf16 v[96:111], v[12:15], v[160:163], v[96:111]
	s_waitcnt lgkmcnt(2)
	v_mfma_f32_32x32x16_bf16 v[80:95], v[240:243], v[160:163], v[80:95]
	v_add_u32_e32 v249, v11, v234
	ds_read_b128 v[12:15], v249
	ds_read_b128 v[240:243], v249 offset:4096
	s_waitcnt lgkmcnt(3)
	v_mfma_f32_32x32x16_bf16 v[96:111], v[2:5], v[152:155], v[96:111]
	s_waitcnt lgkmcnt(2)
	v_mfma_f32_32x32x16_bf16 v[80:95], v[6:9], v[152:155], v[80:95]
	s_waitcnt lgkmcnt(1)
	v_mfma_f32_32x32x16_bf16 v[96:111], v[12:15], v[144:147], v[96:111]
	s_waitcnt lgkmcnt(0)
	v_mfma_f32_32x32x16_bf16 v[80:95], v[240:243], v[144:147], v[80:95]
	v_add_u32_e32 v249, v248, v232
	ds_read_b128 v[2:5], v249 offset:8192
	ds_read_b128 v[6:9], v249 offset:12288
	v_add_u32_e32 v249, v248, v231
	ds_read_b128 v[12:15], v249 offset:8192
	ds_read_b128 v[240:243], v249 offset:12288
	s_nop 3
	v_max3_f32 v244, v96, v97, v98
	v_max3_f32 v245, v107, v108, v109
	v_max3_f32 v247, v86, v87, v88
	v_max3_f32 v244, v244, v99, v100
	v_max3_f32 v245, v245, v110, v111
	v_max3_f32 v247, v247, v89, v90
	v_max3_f32 v244, v244, v101, v102
	v_max3_f32 v245, v245, v80, v81
	v_max3_f32 v247, v247, v91, v92
	v_max3_f32 v244, v244, v103, v104
	v_max3_f32 v245, v245, v82, v83
	v_max3_f32 v247, v247, v93, v94
	v_max3_f32 v244, v244, v105, v106
	v_max3_f32 v245, v245, v84, v85
	v_max_f32_e32 v247, v247, v95
	v_max3_f32 v244, v244, v245, v247
	v_mov_b32_e32 v245, v244
	v_max_f32_e32 v247, v233, v233
	s_nop 0
	v_permlane32_swap_b32_e32 v244, v245
	v_max3_f32 v245, v244, v245, v247
	v_sub_f32_e32 v247, v233, v245
	v_exp_f32_e32 v247, v247
	v_mov_b32_e32 v233, v245
	v_mov_b32_e32 v244, v247
	v_mul_f32_e32 v229, v229, v244
	v_pk_mul_f32 v[32:33], v[32:33], v[244:245] op_sel_hi:[1,0]
	v_pk_mul_f32 v[34:35], v[34:35], v[244:245] op_sel_hi:[1,0]
	v_pk_mul_f32 v[36:37], v[36:37], v[244:245] op_sel_hi:[1,0]
	v_pk_mul_f32 v[38:39], v[38:39], v[244:245] op_sel_hi:[1,0]
	v_pk_mul_f32 v[40:41], v[40:41], v[244:245] op_sel_hi:[1,0]
	v_pk_mul_f32 v[42:43], v[42:43], v[244:245] op_sel_hi:[1,0]
	v_pk_mul_f32 v[44:45], v[44:45], v[244:245] op_sel_hi:[1,0]
	v_pk_mul_f32 v[46:47], v[46:47], v[244:245] op_sel_hi:[1,0]
	v_pk_mul_f32 v[16:17], v[16:17], v[244:245] op_sel_hi:[1,0]
	v_pk_mul_f32 v[18:19], v[18:19], v[244:245] op_sel_hi:[1,0]
	v_pk_mul_f32 v[20:21], v[20:21], v[244:245] op_sel_hi:[1,0]
	v_pk_mul_f32 v[22:23], v[22:23], v[244:245] op_sel_hi:[1,0]
	v_pk_mul_f32 v[24:25], v[24:25], v[244:245] op_sel_hi:[1,0]
	v_pk_mul_f32 v[26:27], v[26:27], v[244:245] op_sel_hi:[1,0]
	v_pk_mul_f32 v[28:29], v[28:29], v[244:245] op_sel_hi:[1,0]
	v_pk_mul_f32 v[30:31], v[30:31], v[244:245] op_sel_hi:[1,0]
	s_branch .Lg2_sm1

; DI int opaque_tid() { int t = threadIdx.x; asm volatile("" : "+v"(t)); return t; }
; template <int DV, bool NA> ...
;   const int tid = opaque_tid(), lane = tid & 63;
;   const int h = lane >> 5, r = lane & 31;
;   bf16x8 q[4];
; #pragma unroll
;   for (int ks = 0; ks < 4; ++ks) q[ks] = *(const bf16x8*)(Qp + ks * 16 + h * 8);
; #pragma unroll
;   for (int mv = 0; mv < DV / 32; ++mv)
; #pragma unroll
;     for (int i = 0; i < 16; ++i) o[mv][i] = 0.f;
;   float m_run = -INFINITY, l_run = 0.f;
;   const int lr = tid >> 3, lc = tid & 7;
;   const int wsw = lr * 128 + ((lc ^ ((lr >> 1) & 7)) << 4);
;   u32x4 rk, rv[DV / 64];
;   auto gload = [&](int ti) {
;     const size_t key0 = (size_t)(tile0 + ti) * 64;
;     rk = *(const u32x4*)(Kb + (key0 + lr) * ldk + lc * 8);
; #pragma unroll
;     for (int i = 0; i < DV / 64; ++i) rv[i] = *(const u32x4*)(Vt + (size_t)(lr + 64 * i) * S + key0 + lc * 8);
;   };
;   auto swrite = [&](int st) {
;     char* ks_ = lds + st * ATT_STAGE;
;     *(u32x4*)(ks_ + wsw) = rk;
; #pragma unroll
;     for (int i = 0; i < DV / 64; ++i) *(u32x4*)(ks_ + 8192 + i * 8192 + wsw) = rv[i];
;   };
;   const int pr = (r & 0x13) | ((r & 4) << 1) | ((r & 8) >> 1);
;   const int ksw = (pr >> 1) & 7;
;   const int vsw = (r >> 1) & 7;
;   const int cs_ = NA ? min(max(qc - 8, 0), 48) : 0;
;   __syncthreads();
;   gload(0);
;   swrite(0);
;   if (ntiles > 1) gload(1);
;   __syncthreads();
; #pragma unroll 2
;   for (int ti = 0; ti < ntiles; ++ti) {
;     if (ti + 1 < ntiles) {
;       swrite((ti + 1) & 1);
;       if (ti + 2 < ntiles) gload(ti + 2);
.LBB0_294:
	v_or_b32_e32 v0, s20, v198
	v_mov_b32_e32 v26, v204
	v_lshlrev_b64 v[2:3], 1, v[0:1]
	v_lshl_add_u64 v[4:5], v[162:163], 0, v[2:3]
	v_bfe_u32 v27, v26, 5, 1
	v_lshl_add_u64 v[2:3], v[160:161], 0, v[2:3]
	v_lshlrev_b32_e32 v0, 4, v27
	v_ashrrev_i32_e32 v14, 3, v26
	v_lshlrev_b32_e32 v28, 4, v26
	v_lshl_add_u64 v[4:5], v[4:5], 0, v[0:1]
	v_ashrrev_i32_e32 v15, 31, v14
	v_mad_i64_i32 v[2:3], s[22:23], v14, s96, v[2:3]
	v_and_b32_e32 v0, 0x70, v28
	v_add_u32_e32 v10, 64, v14
	v_lshl_add_u64 v[16:17], v[2:3], 0, v[0:1]
	v_lshlrev_b64 v[2:3], v176, v[14:15]
	v_ashrrev_i32_e32 v11, 31, v10
	v_lshlrev_b64 v[18:19], 1, v[2:3]
	v_lshlrev_b64 v[10:11], v176, v[10:11]
	v_lshl_add_u64 v[2:3], v[164:165], 0, v[18:19]
	v_lshlrev_b64 v[22:23], 1, v[10:11]
	global_load_dwordx4 v[124:127], v[4:5], off
	global_load_dwordx4 v[120:123], v[4:5], off offset:32
	global_load_dwordx4 v[116:119], v[4:5], off offset:64
	global_load_dwordx4 v[112:115], v[4:5], off offset:96
	s_barrier
	v_lshl_add_u64 v[20:21], v[2:3], 0, v[0:1]
	global_load_dwordx4 v[2:5], v[16:17], off offset:1024
	global_load_dwordx4 v[6:9], v[20:21], off
	v_lshl_add_u64 v[10:11], v[164:165], 0, v[22:23]
	v_lshl_add_u64 v[24:25], v[10:11], 0, v[0:1]
	v_add_co_u32_e32 v16, vcc, s97, v16
	global_load_dwordx4 v[10:13], v[24:25], off
	s_nop 0
	v_addc_co_u32_e32 v17, vcc, 0, v17, vcc
	global_load_dwordx4 v[132:135], v[20:21], off offset:128
	global_load_dwordx4 v[128:131], v[16:17], off offset:1024
	global_load_dwordx4 v[136:139], v[24:25], off offset:128
	v_lshlrev_b32_e32 v15, 1, v26
	v_lshrrev_b32_e32 v20, 1, v26
	v_lshrrev_b32_e32 v16, 5, v26
	v_and_b32_e32 v17, 19, v26
	v_bfe_u32 v21, v26, 1, 3
	v_lshlrev_b32_e32 v24, 7, v26
	v_xor_b32_e32 v26, v28, v26
	v_and_b32_e32 v28, 8, v15
	v_and_b32_e32 v20, 4, v20
	v_bitop3_b32 v16, v16, v21, 1 bitop3:0x6c
	v_or3_b32 v17, v28, v17, v20
	v_lshlrev_b32_e32 v25, 7, v14
	v_and_b32_e32 v178, 0xf80, v24
	v_or_b32_e32 v24, 4, v27
	v_or_b32_e32 v29, 2, v27
	v_or_b32_e32 v30, 6, v27
	v_bitop3_b32 v31, v27, v21, 2 bitop3:0x36
	v_bitop3_b32 v32, v27, v21, 4 bitop3:0x36
	v_bitop3_b32 v21, v27, v21, 6 bitop3:0x36
	v_lshlrev_b32_e32 v195, 4, v16
	v_lshrrev_b32_e32 v16, 1, v17
	v_mad_i64_i32 v[14:15], s[22:23], v14, s96, 0
	v_and_or_b32 v203, v26, s66, v25
	v_lshlrev_b32_e32 v179, 4, v21
	v_lshlrev_b32_e32 v228, 7, v17
	v_bitop3_b32 v20, v16, v27, 7 bitop3:0x6c
	v_bitop3_b32 v21, v16, v29, 7 bitop3:0x6c
	v_bitop3_b32 v24, v16, v24, 7 bitop3:0x6c
	v_bitop3_b32 v25, v16, v30, 7 bitop3:0x6c
	v_lshl_add_u64 v[16:17], v[0:1], 0, v[18:19]
	v_or_b32_e32 v14, v14, v0
	v_lshl_add_u64 v[170:171], v[166:167], 0, v[16:17]
	v_lshl_add_u64 v[16:17], v[0:1], 0, v[22:23]
	v_add_u32_e32 v0, s20, v198
	s_waitcnt vmcnt(18)
	v_lshlrev_b32_e32 v183, 4, v31
	v_lshlrev_b32_e32 v181, 4, v32
	v_lshlrev_b32_e32 v229, 4, v20
	v_lshlrev_b32_e32 v202, 4, v21
	v_lshlrev_b32_e32 v201, 4, v24
	v_lshlrev_b32_e32 v200, 4, v25
	v_lshl_add_u64 v[172:173], v[166:167], 0, v[16:17]
	v_mov_b32_e32 v180, 0
	v_mov_b32_e32 v182, 0xff800000
	s_mov_b64 s[20:21], 0
	s_mov_b32 s31, 0
	s_waitcnt vmcnt(5)
	ds_write_b128 v203, v[2:5]
	s_waitcnt vmcnt(4)
	ds_write_b128 v203, v[6:9] offset:8192
	s_waitcnt vmcnt(3)
	ds_write_b128 v203, v[10:13] offset:16384
	v_lshl_add_u64 v[2:3], v[0:1], 1, v[14:15]
	v_mov_b32_e32 v14, v1
	v_mov_b32_e32 v15, v1
	v_lshl_add_u64 v[174:175], v[168:169], 0, v[2:3]
	v_mov_b32_e32 v0, v1
	v_mov_b32_e32 v2, v1
	v_mov_b32_e32 v3, v1
	v_mov_b32_e32 v4, v1
	v_mov_b32_e32 v5, v1
	v_mov_b32_e32 v6, v1
	v_mov_b32_e32 v7, v1
	v_mov_b32_e32 v8, v1
	v_mov_b32_e32 v9, v1
	v_mov_b32_e32 v10, v1
	v_mov_b32_e32 v11, v1
	v_mov_b32_e32 v12, v1
	v_mov_b32_e32 v13, v1
	v_mov_b64_e32 v[30:31], v[14:15]
	v_mov_b64_e32 v[46:47], v[14:15]
	v_mov_b64_e32 v[62:63], v[14:15]
	v_mov_b64_e32 v[78:79], v[14:15]
	v_mov_b64_e32 v[28:29], v[12:13]
	v_mov_b64_e32 v[26:27], v[10:11]
	v_mov_b64_e32 v[24:25], v[8:9]
	v_mov_b64_e32 v[22:23], v[6:7]
	v_mov_b64_e32 v[20:21], v[4:5]
	v_mov_b64_e32 v[18:19], v[2:3]
	v_mov_b64_e32 v[16:17], v[0:1]
	v_mov_b64_e32 v[44:45], v[12:13]
	v_mov_b64_e32 v[42:43], v[10:11]
	v_mov_b64_e32 v[40:41], v[8:9]
	v_mov_b64_e32 v[38:39], v[6:7]
	v_mov_b64_e32 v[36:37], v[4:5]
	v_mov_b64_e32 v[34:35], v[2:3]
	v_mov_b64_e32 v[32:33], v[0:1]
	v_mov_b64_e32 v[60:61], v[12:13]
	v_mov_b64_e32 v[58:59], v[10:11]
	v_mov_b64_e32 v[56:57], v[8:9]
	v_mov_b64_e32 v[54:55], v[6:7]
	v_mov_b64_e32 v[52:53], v[4:5]
	v_mov_b64_e32 v[50:51], v[2:3]
	v_mov_b64_e32 v[48:49], v[0:1]
	v_mov_b64_e32 v[76:77], v[12:13]
	v_mov_b64_e32 v[74:75], v[10:11]
	v_mov_b64_e32 v[72:73], v[8:9]
	v_mov_b64_e32 v[70:71], v[6:7]
	v_mov_b64_e32 v[68:69], v[4:5]
	v_mov_b64_e32 v[66:67], v[2:3]
	v_mov_b64_e32 v[64:65], v[0:1]
	v_mov_b32_e32 v182, 0
	s_mov_b32 s100, 0xff800000
	v_readfirstlane_b32 s101, v204
	v_mov_b32_e32 v234, 0
	v_mov_b32_e32 v235, 0
	v_mov_b32_e32 v236, 0
	v_mov_b32_e32 v237, 0
	v_mov_b32_e32 v238, 0
	v_mov_b32_e32 v239, 0
	v_mov_b32_e32 v240, 0
	v_mov_b32_e32 v241, 0
	v_mov_b32_e32 v242, 0
	v_mov_b32_e32 v243, 0
	v_mov_b32_e32 v244, 0
	v_mov_b32_e32 v245, 0
	v_mov_b32_e32 v246, 0
	v_mov_b32_e32 v247, 0
	v_mov_b32_e32 v248, 0
	v_mov_b32_e32 v249, 0
	s_lshr_b32 s101, s101, 8
	s_waitcnt lgkmcnt(0)
	s_barrier
	s_branch .LBB0_296
.LBB0_296:
	s_add_i32 s29, s31, 1
	s_bitcmp1_b32 s29, 0
	s_cselect_b32 s30, 0x6000, 0
	s_cmp_eq_u32 s101, 0
	s_cbranch_scc1 .Ldf_skipw_top
	s_add_i32 s22, s31, 2
	v_add_u32_e32 v159, s30, v203
	v_cmp_lt_u32_e32 vcc, s22, v185
	s_waitcnt vmcnt(1)
	ds_write_b128 v159, v[128:131]
	ds_write_b128 v159, v[132:135] offset:8192
	s_waitcnt vmcnt(0)
	ds_write_b128 v159, v[136:139] offset:16384
	s_and_saveexec_b64 s[22:23], vcc
	s_cbranch_execz .Ldf_noload_t
	global_load_dwordx4 v[128:131], v[174:175], off
	global_load_dwordx4 v[132:135], v[170:171], off
	global_load_dwordx4 v[136:139], v[172:173], off
	v_lshl_add_u64 v[170:171], v[170:171], 0, s[4:5]
	v_lshl_add_u64 v[172:173], v[172:173], 0, s[4:5]
	v_lshl_add_u64 v[174:175], v[174:175], 0, s[82:83]

; #define MFMA(a, b, c) __builtin_amdgcn_mfma_f32_32x32x16_bf16((a), (b), (c), 0, 0, 0)
; DI float fexp2(float x) { return __builtin_amdgcn_exp2f(x); }
; template <int DV, bool NA> ...
;     ...
;       {
;         bf16x8 ka[4], kb_[4];
; #pragma unroll
;         for (int ks = 0; ks < 4; ++ks) {
;           const int co = ((2 * ks + h) ^ ksw) << 4;
;           ka[ks] = *(const bf16x8*)(st + pr * 128 + co);
;           kb_[ks] = *(const bf16x8*)(st + (32 + pr) * 128 + co);
;         }
;         asm volatile("" ::: "memory");
; #pragma unroll
;         for (int ks = 0; ks < 4; ++ks) {
;           s0 = MFMA(ka[ks], q[ks], s0);
;           s1 = MFMA(kb_[ks], q[ks], s1);
;         }
;       }
;     ...
;       float ls = 0.f;
; #pragma unroll
;       for (int e = 0; e < 32; ++e) { t[e] = fexp2(t[e] - m_run); ls += t[e]; }
;       l_run += ls;
;       bf16x8 pf[2][2];
; #pragma unroll
;       for (int kb = 0; kb < 2; ++kb)
; #pragma unroll
;         for (int c2 = 0; c2 < 2; ++c2) {
;           const int e0 = kb * 16 + c2 * 8;
;           u32x4 pw = {pk_bf16(t[e0], t[e0 + 1]), pk_bf16(t[e0 + 2], t[e0 + 3]), pk_bf16(t[e0 + 4], t[e0 + 5]), pk_bf16(t[e0 + 6], t[e0 + 7])};
;           pf[kb][c2] = __builtin_bit_cast(bf16x8, pw);
;         }
;       bf16x8 vf1[2][DV / 32];
; #pragma unroll
;       for (int c2 = 0; c2 < 2; ++c2) {
;         const int co = ((4 + 2 * c2 + h) ^ vsw) << 4;
; #pragma unroll
;         for (int mv = 0; mv < DV / 32; ++mv) vf1[c2][mv] = *(const bf16x8*)(st + 8192 + (mv * 32 + r) * 128 + co);
;       }
;       asm volatile("" ::: "memory");
; #pragma unroll
;       for (int c2 = 0; c2 < 2; ++c2)
; #pragma unroll
;         for (int mv = 0; mv < DV / 32; ++mv) o[mv] = MFMA(vf0[c2][mv], pf[0][c2], o[mv]);
; #pragma unroll
;       for (int c2 = 0; c2 < 2; ++c2)
; #pragma unroll
;         for (int mv = 0; mv < DV / 32; ++mv) o[mv] = MFMA(vf1[c2][mv], pf[1][c2], o[mv]);
;     }
;     __syncthreads();
.Ldf_skipw_top:
	s_bitcmp1_b32 s31, 0
	s_cselect_b32 s22, 0x6000, 0
	v_add_u32_e32 v158, s22, v228
	v_add_u32_e32 v159, v158, v229
	ds_read_b128 v[0:3], v159
	ds_read_b128 v[4:7], v159 offset:4096
	v_add_u32_e32 v159, v158, v202
	ds_read_b128 v[8:11], v159
	ds_read_b128 v[12:15], v159 offset:4096
	v_add3_u32 v210, s22, v195, v178
	s_waitcnt lgkmcnt(3)
	v_mfma_f32_32x32x16_bf16 v[96:111], v[0:3], v[124:127], v[234:249]
	s_waitcnt lgkmcnt(2)
	v_mfma_f32_32x32x16_bf16 v[80:95], v[4:7], v[124:127], v[234:249]
	v_add_u32_e32 v159, v158, v201
	ds_read_b128 v[0:3], v159
	ds_read_b128 v[4:7], v159 offset:4096
	s_waitcnt lgkmcnt(3)
	v_mfma_f32_32x32x16_bf16 v[96:111], v[8:11], v[120:123], v[96:111]
	s_waitcnt lgkmcnt(2)
	v_mfma_f32_32x32x16_bf16 v[80:95], v[12:15], v[120:123], v[80:95]
	v_add_u32_e32 v159, v158, v200
	ds_read_b128 v[8:11], v159
	ds_read_b128 v[12:15], v159 offset:4096
	ds_read_b128 v[140:143], v210 offset:8192
	ds_read_b128 v[144:147], v210 offset:12288
	ds_read_b128 v[148:151], v210 offset:16384
	ds_read_b128 v[152:155], v210 offset:20480
	v_add3_u32 v230, s22, v183, v178
	s_waitcnt lgkmcnt(7)
	v_mfma_f32_32x32x16_bf16 v[96:111], v[0:3], v[116:119], v[96:111]
	s_waitcnt lgkmcnt(6)
	v_mfma_f32_32x32x16_bf16 v[80:95], v[4:7], v[116:119], v[80:95]
	s_waitcnt lgkmcnt(5)
	v_mfma_f32_32x32x16_bf16 v[96:111], v[8:11], v[112:115], v[96:111]
	s_waitcnt lgkmcnt(4)
	v_mfma_f32_32x32x16_bf16 v[80:95], v[12:15], v[112:115], v[80:95]
	ds_read_b128 v[0:3], v230 offset:8192
	ds_read_b128 v[4:7], v230 offset:12288
	ds_read_b128 v[8:11], v230 offset:16384
	ds_read_b128 v[12:15], v230 offset:20480
	v_cmp_eq_u32_e32 vcc, s29, v177
	v_add3_u32 v210, s22, v181, v178
	v_add3_u32 v230, s22, v179, v178
	s_or_b64 s[20:21], vcc, s[20:21]
.Ldf_exps:
	s_nop 1
	v_exp_f32_e32 v96, v96
	v_exp_f32_e32 v97, v97
	v_exp_f32_e32 v98, v98
	v_exp_f32_e32 v99, v99
	v_exp_f32_e32 v100, v100
	v_exp_f32_e32 v101, v101
	v_exp_f32_e32 v102, v102
	v_exp_f32_e32 v103, v103
	v_exp_f32_e32 v104, v104
	v_exp_f32_e32 v105, v105
	v_add_f32_e32 v156, v96, v98
	v_add_f32_e32 v157, v97, v99
	v_exp_f32_e32 v106, v106
	v_exp_f32_e32 v107, v107
	v_add_f32_e32 v156, v156, v100
	v_add_f32_e32 v157, v157, v101
	v_exp_f32_e32 v108, v108
	v_exp_f32_e32 v109, v109
	v_add_f32_e32 v156, v156, v102
	v_add_f32_e32 v157, v157, v103
	v_exp_f32_e32 v110, v110
	v_exp_f32_e32 v111, v111
	v_add_f32_e32 v156, v156, v104
	v_add_f32_e32 v157, v157, v105
	v_exp_f32_e32 v80, v80
	v_exp_f32_e32 v81, v81
	v_add_f32_e32 v156, v156, v106
	v_add_f32_e32 v157, v157, v107
	v_exp_f32_e32 v82, v82
	v_exp_f32_e32 v83, v83
	v_add_f32_e32 v156, v156, v108
	v_add_f32_e32 v157, v157, v109
	v_exp_f32_e32 v84, v84
	v_exp_f32_e32 v85, v85
	v_add_f32_e32 v156, v156, v110
	v_add_f32_e32 v157, v157, v111
	v_exp_f32_e32 v86, v86
	v_exp_f32_e32 v87, v87
	v_add_f32_e32 v156, v156, v80
	v_add_f32_e32 v157, v157, v81
	v_exp_f32_e32 v88, v88
	v_exp_f32_e32 v89, v89
	v_add_f32_e32 v156, v156, v82
	v_add_f32_e32 v157, v157, v83
	v_exp_f32_e32 v90, v90
	v_exp_f32_e32 v91, v91
	v_add_f32_e32 v156, v156, v84
	v_add_f32_e32 v157, v157, v85
	v_exp_f32_e32 v92, v92
	v_exp_f32_e32 v93, v93
	v_add_f32_e32 v156, v156, v86
	v_add_f32_e32 v157, v157, v87
	v_exp_f32_e32 v94, v94
	v_exp_f32_e32 v95, v95
	v_add_f32_e32 v156, v156, v88
	v_add_f32_e32 v157, v157, v89
	v_add_f32_e32 v156, v156, v90
	v_add_f32_e32 v157, v157, v91
	v_add_f32_e32 v156, v156, v92
	v_add_f32_e32 v157, v157, v93
	v_add_f32_e32 v156, v156, v94
	v_add_f32_e32 v157, v157, v95
	v_add_f32_e32 v156, v156, v157
	v_cmp_lt_f32_e32 vcc, s100, v156
	s_cbranch_vccnz .Ldf_fix
	v_add_f32_e32 v180, v180, v156
	v_cvt_pk_bf16_f32 v96, v96, v97
	v_cvt_pk_bf16_f32 v97, v98, v99
	v_cvt_pk_bf16_f32 v98, v100, v101
	v_cvt_pk_bf16_f32 v99, v102, v103
	s_waitcnt lgkmcnt(7)
	s_nop 0
	v_mfma_f32_32x32x16_bf16 v[64:79], v[140:143], v[96:99], v[64:79]
	v_cvt_pk_bf16_f32 v104, v104, v105
	s_waitcnt lgkmcnt(6)
	v_mfma_f32_32x32x16_bf16 v[48:63], v[144:147], v[96:99], v[48:63]
	v_cvt_pk_bf16_f32 v105, v106, v107
	s_waitcnt lgkmcnt(5)
	v_mfma_f32_32x32x16_bf16 v[32:47], v[148:151], v[96:99], v[32:47]
	v_cvt_pk_bf16_f32 v106, v108, v109
	s_waitcnt lgkmcnt(4)
	v_mfma_f32_32x32x16_bf16 v[16:31], v[152:155], v[96:99], v[16:31]
	v_cvt_pk_bf16_f32 v107, v110, v111
	ds_read_b128 v[140:143], v210 offset:8192
	ds_read_b128 v[144:147], v210 offset:12288
	ds_read_b128 v[148:151], v210 offset:16384
	ds_read_b128 v[152:155], v210 offset:20480
	s_waitcnt lgkmcnt(7)
	v_mfma_f32_32x32x16_bf16 v[64:79], v[0:3], v[104:107], v[64:79]
	v_cvt_pk_bf16_f32 v80, v80, v81
	s_waitcnt lgkmcnt(6)
	v_mfma_f32_32x32x16_bf16 v[48:63], v[4:7], v[104:107], v[48:63]
	v_cvt_pk_bf16_f32 v81, v82, v83
	s_waitcnt lgkmcnt(5)
	v_mfma_f32_32x32x16_bf16 v[32:47], v[8:11], v[104:107], v[32:47]
	v_cvt_pk_bf16_f32 v82, v84, v85
	s_waitcnt lgkmcnt(4)
	v_mfma_f32_32x32x16_bf16 v[16:31], v[12:15], v[104:107], v[16:31]
	v_cvt_pk_bf16_f32 v83, v86, v87
	ds_read_b128 v[0:3], v230 offset:8192
	ds_read_b128 v[4:7], v230 offset:12288
	ds_read_b128 v[8:11], v230 offset:16384
	ds_read_b128 v[12:15], v230 offset:20480
	s_waitcnt lgkmcnt(7)
	v_mfma_f32_32x32x16_bf16 v[64:79], v[140:143], v[80:83], v[64:79]
	v_cvt_pk_bf16_f32 v88, v88, v89
	s_waitcnt lgkmcnt(6)
	v_mfma_f32_32x32x16_bf16 v[48:63], v[144:147], v[80:83], v[48:63]
	v_cvt_pk_bf16_f32 v89, v90, v91
	s_waitcnt lgkmcnt(5)
	v_mfma_f32_32x32x16_bf16 v[32:47], v[148:151], v[80:83], v[32:47]
	v_cvt_pk_bf16_f32 v90, v92, v93
	s_waitcnt lgkmcnt(4)
	v_mfma_f32_32x32x16_bf16 v[16:31], v[152:155], v[80:83], v[16:31]
	v_cvt_pk_bf16_f32 v91, v94, v95
	s_waitcnt lgkmcnt(3)
	s_nop 0
	v_mfma_f32_32x32x16_bf16 v[64:79], v[0:3], v[88:91], v[64:79]
	s_waitcnt lgkmcnt(2)
	v_mfma_f32_32x32x16_bf16 v[48:63], v[4:7], v[88:91], v[48:63]
	s_waitcnt lgkmcnt(1)
	v_mfma_f32_32x32x16_bf16 v[32:47], v[8:11], v[88:91], v[32:47]
	s_waitcnt lgkmcnt(0)
	v_mfma_f32_32x32x16_bf16 v[16:31], v[12:15], v[88:91], v[16:31]
	s_cmp_eq_u32 s101, 1
	s_cbranch_scc1 .Ldf_skipw_bot
	s_add_i32 s22, s31, 2
	v_add_u32_e32 v159, s30, v203
	v_cmp_lt_u32_e32 vcc, s22, v185
	s_waitcnt vmcnt(1)
	ds_write_b128 v159, v[128:131]
	ds_write_b128 v159, v[132:135] offset:8192
	s_waitcnt vmcnt(0)
	ds_write_b128 v159, v[136:139] offset:16384
	s_and_saveexec_b64 s[22:23], vcc
	s_cbranch_execz .Ldf_noload_b
	global_load_dwordx4 v[128:131], v[174:175], off
	global_load_dwordx4 v[132:135], v[170:171], off
	global_load_dwordx4 v[136:139], v[172:173], off
	v_lshl_add_u64 v[170:171], v[170:171], 0, s[4:5]
	v_lshl_add_u64 v[172:173], v[172:173], 0, s[4:5]
	v_lshl_add_u64 v[174:175], v[174:175], 0, s[82:83]

; DI float fexp2(float x) { return __builtin_amdgcn_exp2f(x); }
; template <int DV, bool NA> ...
;     ...
;       float mx = t[0];
; #pragma unroll
;       for (int e = 1; e < 32; ++e) mx = fmaxf(mx, t[e]);
;       mx = fmaxf(mx, __shfl_xor(mx, 32));
;       if (__builtin_amdgcn_ballot_w64(mx > m_run + 8.f) != 0ull) {
;         const float m_new = fmaxf(m_run, mx);
;         const float alpha = fexp2(m_run - m_new);
;         l_run *= alpha;
;         m_run = m_new;
; #pragma unroll
;         for (int mv = 0; mv < DV / 32; ++mv)
; #pragma unroll
;           for (int i = 0; i < 16; ++i) o[mv][i] *= alpha;
;       }
.Ldf_skipw_bot:
	v_mov_b32_e32 v0, s30
	v_mov_b32_e32 v1, 0
	s_mov_b32 s31, s29
	s_waitcnt lgkmcnt(0)
	s_barrier
	s_andn2_b64 exec, exec, s[20:21]
	s_cbranch_execnz .LBB0_296
	s_branch .LBB0_300
.Ldf_fix:
	s_waitcnt lgkmcnt(0)
	v_add_u32_e32 v158, s22, v228
	v_add_u32_e32 v159, v158, v229
	ds_read_b128 v[0:3], v159
	ds_read_b128 v[4:7], v159 offset:4096
	v_add_u32_e32 v159, v158, v202
	ds_read_b128 v[8:11], v159
	ds_read_b128 v[12:15], v159 offset:4096
	s_waitcnt lgkmcnt(3)
	v_mfma_f32_32x32x16_bf16 v[96:111], v[0:3], v[124:127], v[234:249]
	s_waitcnt lgkmcnt(2)
	v_mfma_f32_32x32x16_bf16 v[80:95], v[4:7], v[124:127], v[234:249]
	v_add_u32_e32 v159, v158, v201
	ds_read_b128 v[0:3], v159
	ds_read_b128 v[4:7], v159 offset:4096
	s_waitcnt lgkmcnt(3)
	v_mfma_f32_32x32x16_bf16 v[96:111], v[8:11], v[120:123], v[96:111]
	s_waitcnt lgkmcnt(2)
	v_mfma_f32_32x32x16_bf16 v[80:95], v[12:15], v[120:123], v[80:95]
	v_add_u32_e32 v159, v158, v200
	ds_read_b128 v[8:11], v159
	ds_read_b128 v[12:15], v159 offset:4096
	v_add3_u32 v230, s22, v183, v178
	s_waitcnt lgkmcnt(3)
	v_mfma_f32_32x32x16_bf16 v[96:111], v[0:3], v[116:119], v[96:111]
	s_waitcnt lgkmcnt(2)
	v_mfma_f32_32x32x16_bf16 v[80:95], v[4:7], v[116:119], v[80:95]
	s_waitcnt lgkmcnt(1)
	v_mfma_f32_32x32x16_bf16 v[96:111], v[8:11], v[112:115], v[96:111]
	s_waitcnt lgkmcnt(0)
	v_mfma_f32_32x32x16_bf16 v[80:95], v[12:15], v[112:115], v[80:95]
	ds_read_b128 v[0:3], v230 offset:8192
	ds_read_b128 v[4:7], v230 offset:12288
	ds_read_b128 v[8:11], v230 offset:16384
	ds_read_b128 v[12:15], v230 offset:20480
	s_nop 5
	v_max3_f32 v156, v96, v97, v98
	v_max3_f32 v157, v105, v106, v107
	v_max3_f32 v158, v80, v81, v82
	v_max3_f32 v159, v89, v90, v91
	v_max3_f32 v156, v156, v99, v100
	v_max3_f32 v157, v157, v108, v109
	v_max3_f32 v158, v158, v83, v84
	v_max3_f32 v159, v159, v92, v93
	v_max3_f32 v156, v156, v101, v102
	v_max3_f32 v157, v157, v110, v111
	v_max3_f32 v158, v158, v85, v86
	v_max3_f32 v159, v159, v94, v95
	v_max3_f32 v156, v156, v103, v104
	v_max3_f32 v158, v158, v87, v88
	v_max3_f32 v156, v156, v157, v158
	v_max_f32_e32 v156, v156, v159
	v_mov_b32_e32 v157, v156
	v_mov_b32_e32 v158, s100
	s_nop 0
	v_permlane32_swap_b32_e32 v156, v157
	v_max_f32_e32 v156, v156, v157
	v_max_f32_e32 v158, 0xff800000, v158
	v_cmp_class_f32_e64 vcc, v158, 4
	v_max_f32_e32 v157, 0, v156
	s_nop 1
	v_cndmask_b32_e32 v157, v157, v156, vcc
	s_mov_b32 s100, 0x5d800000
	v_add_f32_e32 v182, v182, v157
	v_min_f32_e64 v158, -v157, 0
	v_exp_f32_e32 v158, v158
	v_sub_f32_e32 v234, v234, v157
	v_sub_f32_e32 v235, v235, v157
	v_sub_f32_e32 v236, v236, v157
	v_sub_f32_e32 v237, v237, v157
	v_sub_f32_e32 v238, v238, v157
	v_sub_f32_e32 v239, v239, v157
	v_sub_f32_e32 v240, v240, v157
	v_sub_f32_e32 v241, v241, v157
	v_sub_f32_e32 v242, v242, v157
	v_sub_f32_e32 v243, v243, v157
	v_sub_f32_e32 v244, v244, v157
	v_sub_f32_e32 v245, v245, v157
	v_sub_f32_e32 v246, v246, v157
	v_sub_f32_e32 v247, v247, v157
	v_sub_f32_e32 v248, v248, v157
	v_sub_f32_e32 v249, v249, v157
	v_sub_f32_e32 v80, v80, v157
	v_sub_f32_e32 v81, v81, v157
	v_sub_f32_e32 v82, v82, v157
	v_sub_f32_e32 v83, v83, v157
	v_sub_f32_e32 v84, v84, v157
	v_sub_f32_e32 v85, v85, v157
	v_sub_f32_e32 v86, v86, v157
	v_sub_f32_e32 v87, v87, v157
	v_sub_f32_e32 v88, v88, v157
	v_sub_f32_e32 v89, v89, v157
	v_sub_f32_e32 v90, v90, v157
	v_sub_f32_e32 v91, v91, v157
	v_sub_f32_e32 v92, v92, v157
	v_sub_f32_e32 v93, v93, v157
	v_sub_f32_e32 v94, v94, v157
	v_sub_f32_e32 v95, v95, v157
	v_sub_f32_e32 v96, v96, v157
	v_sub_f32_e32 v97, v97, v157
	v_sub_f32_e32 v98, v98, v157
	v_sub_f32_e32 v99, v99, v157
	v_sub_f32_e32 v100, v100, v157
	v_sub_f32_e32 v101, v101, v157
	v_sub_f32_e32 v102, v102, v157
	v_sub_f32_e32 v103, v103, v157
	v_sub_f32_e32 v104, v104, v157
	v_sub_f32_e32 v105, v105, v157
	v_sub_f32_e32 v106, v106, v157
	v_sub_f32_e32 v107, v107, v157
	v_sub_f32_e32 v108, v108, v157
	v_sub_f32_e32 v109, v109, v157
	v_sub_f32_e32 v110, v110, v157
	v_sub_f32_e32 v111, v111, v157
	v_pk_mul_f32 v[16:17], v[16:17], v[158:159] op_sel_hi:[1,0]
	v_pk_mul_f32 v[18:19], v[18:19], v[158:159] op_sel_hi:[1,0]
	v_pk_mul_f32 v[20:21], v[20:21], v[158:159] op_sel_hi:[1,0]
	v_pk_mul_f32 v[22:23], v[22:23], v[158:159] op_sel_hi:[1,0]
	v_pk_mul_f32 v[24:25], v[24:25], v[158:159] op_sel_hi:[1,0]
	v_pk_mul_f32 v[26:27], v[26:27], v[158:159] op_sel_hi:[1,0]
	v_pk_mul_f32 v[28:29], v[28:29], v[158:159] op_sel_hi:[1,0]
	v_pk_mul_f32 v[30:31], v[30:31], v[158:159] op_sel_hi:[1,0]
	v_pk_mul_f32 v[32:33], v[32:33], v[158:159] op_sel_hi:[1,0]
	v_pk_mul_f32 v[34:35], v[34:35], v[158:159] op_sel_hi:[1,0]
	v_pk_mul_f32 v[36:37], v[36:37], v[158:159] op_sel_hi:[1,0]
	v_pk_mul_f32 v[38:39], v[38:39], v[158:159] op_sel_hi:[1,0]
	v_pk_mul_f32 v[40:41], v[40:41], v[158:159] op_sel_hi:[1,0]
	v_pk_mul_f32 v[42:43], v[42:43], v[158:159] op_sel_hi:[1,0]
	v_pk_mul_f32 v[44:45], v[44:45], v[158:159] op_sel_hi:[1,0]
	v_pk_mul_f32 v[46:47], v[46:47], v[158:159] op_sel_hi:[1,0]
	v_pk_mul_f32 v[48:49], v[48:49], v[158:159] op_sel_hi:[1,0]
	v_pk_mul_f32 v[50:51], v[50:51], v[158:159] op_sel_hi:[1,0]
	v_pk_mul_f32 v[52:53], v[52:53], v[158:159] op_sel_hi:[1,0]
	v_pk_mul_f32 v[54:55], v[54:55], v[158:159] op_sel_hi:[1,0]
	v_pk_mul_f32 v[56:57], v[56:57], v[158:159] op_sel_hi:[1,0]
	v_pk_mul_f32 v[58:59], v[58:59], v[158:159] op_sel_hi:[1,0]
	v_pk_mul_f32 v[60:61], v[60:61], v[158:159] op_sel_hi:[1,0]
	v_pk_mul_f32 v[62:63], v[62:63], v[158:159] op_sel_hi:[1,0]
	v_pk_mul_f32 v[64:65], v[64:65], v[158:159] op_sel_hi:[1,0]
	v_pk_mul_f32 v[66:67], v[66:67], v[158:159] op_sel_hi:[1,0]
	v_pk_mul_f32 v[68:69], v[68:69], v[158:159] op_sel_hi:[1,0]
	v_pk_mul_f32 v[70:71], v[70:71], v[158:159] op_sel_hi:[1,0]
	v_pk_mul_f32 v[72:73], v[72:73], v[158:159] op_sel_hi:[1,0]
	v_pk_mul_f32 v[74:75], v[74:75], v[158:159] op_sel_hi:[1,0]
	v_pk_mul_f32 v[76:77], v[76:77], v[158:159] op_sel_hi:[1,0]
	v_pk_mul_f32 v[78:79], v[78:79], v[158:159] op_sel_hi:[1,0]
	v_mul_f32_e32 v180, v180, v158
	v_add3_u32 v230, s22, v179, v178
	s_branch .Ldf_exps
